# attention computed transposed (S^T = K Q^T, O^T = V^T P^T): P stays in registers as the MFMA B operand, key rows taken in permuted order so V keeps 16-byte loads; row max/sum across lanes by permlane
# speedup vs baseline: 1.0047x; 1.0047x over previous
.LBB0_459:
	v_mov_b32_e32 v37, v189
	s_mov_b32 s0, s33
	s_lshl_b32 s1, s0, 8
	s_and_b32 s1, s1, 0x700
	s_add_i32 s1, s1, s0
	s_and_b32 s4, s1, -8
	s_lshl_b32 s0, s89, 11
	s_add_i32 s2, s4, s0
	s_ashr_i32 s1, s2, 13
	s_lshl_b32 s3, s1, 8
	s_add_i32 s3, s3, 0x8000
	v_ashrrev_i32_e32 v46, 3, v37
	v_add_u32_e32 v4, s3, v46
	v_add_u32_e32 v22, 0x200, v37
	v_ashrrev_i32_e32 v5, 31, v4
	v_ashrrev_i32_e32 v48, 3, v22
	s_bfe_u32 s0, s2, 0x40009
	v_lshlrev_b64 v[4:5], 13, v[4:5]
	v_add_u32_e32 v6, s3, v48
	v_add_u32_e32 v28, 0x400, v37
	v_lshlrev_b32_e32 v20, 4, v37
	v_lshl_add_u64 v[4:5], s[60:61], 0, v[4:5]
	s_lshl_b32 s36, s0, 7
	v_ashrrev_i32_e32 v7, 31, v6
	v_ashrrev_i32_e32 v49, 3, v28
	v_and_b32_e32 v124, 0x70, v20
	v_lshl_add_u64 v[4:5], v[4:5], 0, s[36:37]
	v_lshlrev_b64 v[6:7], 13, v[6:7]
	v_add_u32_e32 v12, s3, v49
	v_add_u32_e32 v34, 0x600, v37
	v_lshl_add_u64 v[4:5], v[4:5], 0, v[124:125]
	v_lshl_add_u64 v[6:7], s[60:61], 0, v[6:7]
	v_ashrrev_i32_e32 v13, 31, v12
	v_ashrrev_i32_e32 v50, 3, v34
	v_add_co_u32_e32 v4, vcc, s66, v4
	v_lshl_add_u64 v[6:7], v[6:7], 0, s[36:37]
	v_lshlrev_b64 v[12:13], 13, v[12:13]
	v_add_u32_e32 v14, s3, v50
	v_addc_co_u32_e32 v5, vcc, 0, v5, vcc
	v_lshl_add_u64 v[6:7], v[6:7], 0, v[124:125]
	v_lshl_add_u64 v[12:13], s[60:61], 0, v[12:13]
	v_ashrrev_i32_e32 v15, 31, v14
	v_add_co_u32_e32 v8, vcc, s66, v6
	v_lshl_add_u64 v[12:13], v[12:13], 0, s[36:37]
	v_lshlrev_b64 v[14:15], 13, v[14:15]
	v_addc_co_u32_e32 v9, vcc, 0, v7, vcc
	v_lshl_add_u64 v[12:13], v[12:13], 0, v[124:125]
	v_lshl_add_u64 v[14:15], s[60:61], 0, v[14:15]
	s_lshl_b32 s1, s1, 4
	v_add_co_u32_e32 v12, vcc, s66, v12
	v_lshl_add_u64 v[14:15], v[14:15], 0, s[36:37]
	s_or_b32 s0, s1, s0
	v_addc_co_u32_e32 v13, vcc, 0, v13, vcc
	v_lshl_add_u64 v[14:15], v[14:15], 0, v[124:125]
	s_ashr_i32 s1, s0, 31
	s_barrier
	s_bfe_u32 s5, s2, 0x40009
	s_mul_i32 s5, s5, 0x744
	v_lshlrev_b32_e32 v56, 2, v189
	s_add_u32 s6, s48, s5
	s_addc_u32 s7, s49, 0
	v_cmp_gt_u32_e32 vcc, 0x744, v56
	s_and_saveexec_b64 s[8:9], vcc
	global_load_dword v57, v56, s[6:7]
	s_or_b64 exec, exec, s[8:9]
	global_load_dwordx4 v[4:7], v[4:5], off
	s_nop 0
	global_load_dwordx4 v[8:11], v[8:9], off
	v_add_co_u32_e32 v16, vcc, s66, v14
	s_lshl_b64 s[0:1], s[0:1], 15
	s_nop 0
	v_addc_co_u32_e32 v17, vcc, 0, v15, vcc
	s_add_u32 s0, s46, s0
	v_ashrrev_i32_e32 v38, 5, v37
	v_ashrrev_i32_e32 v40, 5, v22
	v_add_u32_e32 v36, 0, v124
	global_load_dwordx4 v[12:15], v[12:13], off
	s_nop 0
	global_load_dwordx4 v[16:19], v[16:17], off
	s_addc_u32 s1, s47, s1
	v_and_b32_e32 v124, 0x1f0, v20
	v_ashrrev_i32_e32 v39, 31, v38
	v_ashrrev_i32_e32 v41, 31, v40
	v_ashrrev_i32_e32 v42, 5, v28
	v_ashrrev_i32_e32 v44, 5, v34
	v_lshl_add_u64 v[32:33], s[0:1], 0, v[124:125]
	v_lshlrev_b64 v[20:21], 9, v[38:39]
	v_lshlrev_b64 v[22:23], 9, v[40:41]
	v_ashrrev_i32_e32 v43, 31, v42
	v_ashrrev_i32_e32 v45, 31, v44
	v_lshl_add_u64 v[20:21], v[32:33], 0, v[20:21]
	v_lshl_add_u64 v[24:25], v[32:33], 0, v[22:23]
	v_lshlrev_b64 v[28:29], 9, v[42:43]
	v_lshlrev_b64 v[34:35], 9, v[44:45]
	global_load_dwordx4 v[20:23], v[20:21], off
	s_nop 0
	global_load_dwordx4 v[24:27], v[24:25], off
	v_lshl_add_u64 v[28:29], v[32:33], 0, v[28:29]
	v_lshl_add_u64 v[32:33], v[32:33], 0, v[34:35]
	global_load_dwordx4 v[28:31], v[28:29], off
	v_mad_u64_u32 v[46:47], s[0:1], v46, s67, v[36:37]
	global_load_dwordx4 v[32:35], v[32:33], off
	v_mov_b32_e32 v129, v125
	v_mov_b32_e32 v141, v125
	v_mov_b32_e32 v139, v125
	v_mov_b32_e32 v39, v125
	s_add_i32 s4, s4, s88
	v_mov_b32_e32 v47, v125
	s_mov_b32 s36, 1
	s_mov_b32 s90, 0
	v_mov_b32_e32 v170, 0xf149f2ca
	v_mov_b32_e32 v171, 0xf149f2ca
	v_mov_b32_e32 v172, 0xf149f2ca
	v_mov_b32_e32 v198, 0xf149f2ca
	s_mov_b32 s91, 0
	v_mov_b32_e32 v152, v125
	v_mov_b32_e32 v153, v125
	v_mov_b32_e32 v154, v125
	v_mov_b32_e32 v155, v125
	s_waitcnt vmcnt(7)
	ds_write_b128 v46, v[4:7] offset:20480
	v_mad_u64_u32 v[4:5], s[0:1], v48, s67, v[36:37]
	s_waitcnt vmcnt(6)
	ds_write_b128 v4, v[8:11] offset:20480
	v_mad_u64_u32 v[4:5], s[0:1], v49, s67, v[36:37]
	s_waitcnt vmcnt(5)
	ds_write_b128 v4, v[12:15] offset:20480
	v_mad_u64_u32 v[4:5], s[0:1], v50, s67, v[36:37]
	s_waitcnt vmcnt(4)
	ds_write_b128 v4, v[16:19] offset:20480
	v_add_u32_e32 v4, 0, v124
	v_mad_u64_u32 v[6:7], s[0:1], v38, s86, v[4:5]
	v_ashrrev_i32_e32 v50, 6, v37
	s_waitcnt vmcnt(3)
	ds_write_b128 v6, v[20:23] offset:57344
	v_mad_u64_u32 v[6:7], s[0:1], v40, s86, v[4:5]
	s_waitcnt vmcnt(2)
	ds_write_b128 v6, v[24:27] offset:57344
	v_mad_u64_u32 v[6:7], s[0:1], v42, s86, v[4:5]
	v_mad_u64_u32 v[4:5], s[0:1], v44, s86, v[4:5]
	s_waitcnt vmcnt(1)
	ds_write_b128 v6, v[28:31] offset:57344
	s_waitcnt vmcnt(0)
	ds_write_b128 v4, v[32:35] offset:57344
	v_add_u32_e32 v4, s2, v50
	s_movk_i32 s0, 0xa00
	v_mul_lo_u32 v5, v50, s0
	v_ashrrev_i32_e32 v44, 13, v4
	v_add_u32_e32 v51, 0, v5
	v_mov_b32_e32 v5, v189
	v_ashrrev_i32_e32 v45, 31, v44
	v_lshlrev_b32_e32 v6, 4, v50
	v_cmp_gt_u32_e32 vcc, 0x744, v56
	v_add_u32_e32 v58, 0x16400, v56
	s_and_saveexec_b64 s[8:9], vcc
	ds_write_b32 v58, v57
	s_or_b64 exec, exec, s[8:9]
	s_waitcnt lgkmcnt(0)
	s_barrier
	v_and_b32_e32 v191, 15, v189
	v_bfe_u32 v192, v189, 4, 2
	v_lshrrev_b32_e32 v199, 6, v189
	v_mov_b32_e32 v203, 0
	v_mov_b32_e32 v214, 0x3e000000
	v_mov_b32_e32 v215, 0x3fb8aa3b
	s_add_u32 s8, s52, 0x3e5000c8
	s_addc_u32 s9, s53, 0
	v_readfirstlane_b32 s0, v199
	v_lshlrev_b32_e32 v193, 13, v191
	v_lshlrev_b32_e32 v200, 4, v192
	v_mov_b32_e32 v201, s8
	v_mov_b32_e32 v202, s9
	s_nop 0
	v_add_u32_e32 v193, v193, v200
	v_lshlrev_b32_e32 v201, 3, v192
	v_lshlrev_b32_e32 v204, 14, v191
	v_add_u32_e32 v204, v204, v200
	v_add_u32_e32 v205, 0x40000, v204
	v_add_u32_e32 v206, 0x80000, v204
	v_add_u32_e32 v207, 0xc0000, v204
	v_mul_u32_u24_e32 v194, 144, v191
	v_add_u32_e32 v194, v194, v200
	v_add_u32_e32 v194, 0x5000, v194
	v_mul_u32_u24_e32 v195, 0x210, v191
	v_add_u32_e32 v195, v195, v200
	v_add_u32_e32 v195, 0xe000, v195
	v_lshrrev_b32_e32 v202, 2, v191
	v_and_b32_e32 v199, 3, v191
	v_lshl_add_u32 v202, v202, 3, v199
	v_lshl_add_u32 v208, v202, 13, v200
	v_add_u32_e32 v209, 0x8000, v208
	v_mul_u32_u24_e32 v210, 144, v202
	v_add_u32_e32 v210, v210, v200
	v_add_u32_e32 v210, 0x5000, v210
	v_add_u32_e32 v211, 576, v210
	v_lshlrev_b32_e32 v198, 12, v191
	v_add_u32_e32 v198, v198, v201
	s_add_u32 s0, s0, s2
	s_and_b32 s1, s0, 3
	s_bfe_u32 s3, s0, 0x70002
	s_bfe_u32 s4, s0, 0x40009
	s_lshr_b32 s5, s0, 13
	s_sub_u32 s6, s3, 4
	s_max_i32 s6, s6, 0
	s_min_i32 s6, s6, 0x78
	s_lshl_b32 s7, s1, 4
	s_sub_u32 s7, s7, 8
	s_max_i32 s7, s7, 0
	s_min_i32 s7, s7, 32
	s_lshl_b32 s8, s5, 26
	s_lshl_b32 s9, s4, 7
	s_add_u32 s8, s8, s9
	s_add_u32 s16, s60, s8
	s_addc_u32 s17, s61, 0
	s_lshl_b32 s8, s3, 6
	s_lshl_b32 s9, s1, 4
	s_add_u32 s8, s8, s9
	s_lshl_b32 s9, s8, 13
	s_add_u32 s9, s9, 0x800
	s_add_u32 s14, s16, s9
	s_addc_u32 s15, s17, 0
	global_load_dwordx4 v[4:7], v193, s[14:15]
	global_load_dwordx4 v[8:11], v193, s[14:15] offset:64
	s_lshl_b32 s9, s5, 13
	s_add_u32 s8, s8, s9
	s_lshl_b32 s8, s8, 12
	s_lshl_b32 s9, s4, 7
	s_add_u32 s8, s8, s9
	s_add_u32 s8, s8, 0x34c00800
	s_add_u32 s20, s52, s8
	s_addc_u32 s21, s53, 0
	s_add_u32 s16, s16, 0x1000
	s_addc_u32 s17, s17, 0
	s_lshl_b32 s8, s5, 4
	s_add_u32 s8, s8, s4
	s_lshl_b32 s8, s8, 20
	s_add_u32 s8, s8, 0x2ea00000
	s_add_u32 s18, s52, s8
	s_addc_u32 s19, s53, 0
	s_add_u32 s8, s6, 0
	s_lshl_b32 s8, s8, 6
	s_add_u32 s8, s8, s7
	s_lshl_b32 s8, s8, 13
	s_add_u32 s22, s16, s8
	s_addc_u32 s23, s17, 0
	global_load_dwordx4 v[12:15], v208, s[22:23]
	global_load_dwordx4 v[16:19], v208, s[22:23] offset:64
	s_add_u32 s8, s6, 0
	s_lshl_b32 s8, s8, 6
	s_add_u32 s8, s8, s7
	s_lshl_b32 s8, s8, 13
	s_add_u32 s22, s16, s8
	s_addc_u32 s23, s17, 0
	global_load_dwordx4 v[20:23], v209, s[22:23]
	global_load_dwordx4 v[24:27], v209, s[22:23] offset:64
	s_add_u32 s8, s6, 1
	s_lshl_b32 s8, s8, 6
	s_add_u32 s8, s8, s7
	s_lshl_b32 s8, s8, 13
	s_add_u32 s22, s16, s8
	s_addc_u32 s23, s17, 0
	global_load_dwordx4 v[28:31], v208, s[22:23]
	global_load_dwordx4 v[32:35], v208, s[22:23] offset:64
	s_add_u32 s8, s6, 1
	s_lshl_b32 s8, s8, 6
	s_add_u32 s8, s8, s7
	s_lshl_b32 s8, s8, 13
	s_add_u32 s22, s16, s8
	s_addc_u32 s23, s17, 0
	global_load_dwordx4 v[36:39], v209, s[22:23]
	global_load_dwordx4 v[40:43], v209, s[22:23] offset:64
	s_sub_u32 s11, s6, s3
	s_add_u32 s11, s11, 7
	s_mul_i32 s11, s11, 124
	s_add_u32 s11, s11, 0x16400
	v_lshlrev_b32_e32 v199, 3, v192
	v_sub_u32_e32 v199, v199, v191
	s_lshl_b32 s8, s1, 4
	s_sub_i32 s9, s7, s8
	s_add_i32 s9, s9, 15
	v_add_u32_e32 v200, s9, v199
	v_med3_i32 v200, v200, 0, 30
	v_lshl_add_u32 v172, v200, 2, s11
	v_add_u32_e32 v200, s8, v191
	v_add_u32_e32 v200, -8, v200
	v_med3_i32 v200, v200, 0, 48
	v_lshlrev_b32_e32 v201, 3, v192
	v_add_u32_e32 v201, s7, v201
	v_add_u32_e32 v201, 0, v201
	v_sub_u32_e32 v201, v201, v200
	v_mov_b32_e32 v202, 0xf149f2ca
	v_cmp_gt_u32_e32 vcc, 16, v201
	s_nop 1
	v_cndmask_b32_e32 v180, v202, v203, vcc
	v_lshlrev_b32_e32 v199, 3, v192
	v_sub_u32_e32 v199, v199, v191
	s_lshl_b32 s8, s1, 4
	s_sub_i32 s9, s7, s8
	s_add_i32 s9, s9, 16
	v_add_u32_e32 v200, s9, v199
	v_med3_i32 v200, v200, 0, 30
	v_lshl_add_u32 v173, v200, 2, s11
	v_add_u32_e32 v200, s8, v191
	v_add_u32_e32 v200, -8, v200
	v_med3_i32 v200, v200, 0, 48
	v_lshlrev_b32_e32 v201, 3, v192
	v_add_u32_e32 v201, s7, v201
	v_add_u32_e32 v201, 1, v201
	v_sub_u32_e32 v201, v201, v200
	v_mov_b32_e32 v202, 0xf149f2ca
	v_cmp_gt_u32_e32 vcc, 16, v201
	s_nop 1
	v_cndmask_b32_e32 v181, v202, v203, vcc
	v_lshlrev_b32_e32 v199, 3, v192
	v_sub_u32_e32 v199, v199, v191
	s_lshl_b32 s8, s1, 4
	s_sub_i32 s9, s7, s8
	s_add_i32 s9, s9, 17
	v_add_u32_e32 v200, s9, v199
	v_med3_i32 v200, v200, 0, 30
	v_lshl_add_u32 v174, v200, 2, s11
	v_add_u32_e32 v200, s8, v191
	v_add_u32_e32 v200, -8, v200
	v_med3_i32 v200, v200, 0, 48
	v_lshlrev_b32_e32 v201, 3, v192
	v_add_u32_e32 v201, s7, v201
	v_add_u32_e32 v201, 2, v201
	v_sub_u32_e32 v201, v201, v200
	v_mov_b32_e32 v202, 0xf149f2ca
	v_cmp_gt_u32_e32 vcc, 16, v201
	s_nop 1
	v_cndmask_b32_e32 v182, v202, v203, vcc
	v_lshlrev_b32_e32 v199, 3, v192
	v_sub_u32_e32 v199, v199, v191
	s_lshl_b32 s8, s1, 4
	s_sub_i32 s9, s7, s8
	s_add_i32 s9, s9, 18
	v_add_u32_e32 v200, s9, v199
	v_med3_i32 v200, v200, 0, 30
	v_lshl_add_u32 v175, v200, 2, s11
	v_add_u32_e32 v200, s8, v191
	v_add_u32_e32 v200, -8, v200
	v_med3_i32 v200, v200, 0, 48
	v_lshlrev_b32_e32 v201, 3, v192
	v_add_u32_e32 v201, s7, v201
	v_add_u32_e32 v201, 3, v201
	v_sub_u32_e32 v201, v201, v200
	v_mov_b32_e32 v202, 0xf149f2ca
	v_cmp_gt_u32_e32 vcc, 16, v201
	s_nop 1
	v_cndmask_b32_e32 v183, v202, v203, vcc
	v_lshlrev_b32_e32 v199, 3, v192
	v_sub_u32_e32 v199, v199, v191
	s_lshl_b32 s8, s1, 4
	s_sub_i32 s9, s7, s8
	s_add_i32 s9, s9, 19
	v_add_u32_e32 v200, s9, v199
	v_med3_i32 v200, v200, 0, 30
	v_lshl_add_u32 v176, v200, 2, s11
	v_add_u32_e32 v200, s8, v191
	v_add_u32_e32 v200, -8, v200
	v_med3_i32 v200, v200, 0, 48
	v_lshlrev_b32_e32 v201, 3, v192
	v_add_u32_e32 v201, s7, v201
	v_add_u32_e32 v201, 4, v201
	v_sub_u32_e32 v201, v201, v200
	v_mov_b32_e32 v202, 0xf149f2ca
	v_cmp_gt_u32_e32 vcc, 16, v201
	s_nop 1
	v_cndmask_b32_e32 v184, v202, v203, vcc
	v_lshlrev_b32_e32 v199, 3, v192
	v_sub_u32_e32 v199, v199, v191
	s_lshl_b32 s8, s1, 4
	s_sub_i32 s9, s7, s8
	s_add_i32 s9, s9, 20
	v_add_u32_e32 v200, s9, v199
	v_med3_i32 v200, v200, 0, 30
	v_lshl_add_u32 v177, v200, 2, s11
	v_add_u32_e32 v200, s8, v191
	v_add_u32_e32 v200, -8, v200
	v_med3_i32 v200, v200, 0, 48
	v_lshlrev_b32_e32 v201, 3, v192
	v_add_u32_e32 v201, s7, v201
	v_add_u32_e32 v201, 5, v201
	v_sub_u32_e32 v201, v201, v200
	v_mov_b32_e32 v202, 0xf149f2ca
	v_cmp_gt_u32_e32 vcc, 16, v201
	s_nop 1
	v_cndmask_b32_e32 v185, v202, v203, vcc
	v_lshlrev_b32_e32 v199, 3, v192
	v_sub_u32_e32 v199, v199, v191
	s_lshl_b32 s8, s1, 4
	s_sub_i32 s9, s7, s8
	s_add_i32 s9, s9, 21
	v_add_u32_e32 v200, s9, v199
	v_med3_i32 v200, v200, 0, 30
	v_lshl_add_u32 v178, v200, 2, s11
	v_add_u32_e32 v200, s8, v191
	v_add_u32_e32 v200, -8, v200
	v_med3_i32 v200, v200, 0, 48
	v_lshlrev_b32_e32 v201, 3, v192
	v_add_u32_e32 v201, s7, v201
	v_add_u32_e32 v201, 6, v201
	v_sub_u32_e32 v201, v201, v200
	v_mov_b32_e32 v202, 0xf149f2ca
	v_cmp_gt_u32_e32 vcc, 16, v201
	s_nop 1
	v_cndmask_b32_e32 v186, v202, v203, vcc
	v_lshlrev_b32_e32 v199, 3, v192
	v_sub_u32_e32 v199, v199, v191
	s_lshl_b32 s8, s1, 4
	s_sub_i32 s9, s7, s8
	s_add_i32 s9, s9, 22
	v_add_u32_e32 v200, s9, v199
	v_med3_i32 v200, v200, 0, 30
	v_lshl_add_u32 v179, v200, 2, s11
	v_add_u32_e32 v200, s8, v191
	v_add_u32_e32 v200, -8, v200
	v_med3_i32 v200, v200, 0, 48
	v_lshlrev_b32_e32 v201, 3, v192
	v_add_u32_e32 v201, s7, v201
	v_add_u32_e32 v201, 7, v201
	v_sub_u32_e32 v201, v201, v200
	v_mov_b32_e32 v202, 0xf149f2ca
	v_cmp_gt_u32_e32 vcc, 16, v201
	s_nop 1
	v_cndmask_b32_e32 v187, v202, v203, vcc
	v_mov_b32_e32 v80, 0xf149f2ca
	v_mov_b32_e32 v81, 0
	v_mov_b32_e32 v100, 0
	v_mov_b32_e32 v101, 0
	v_mov_b32_e32 v102, 0
	v_mov_b32_e32 v103, 0
	v_mov_b32_e32 v132, 0
	v_mov_b32_e32 v133, 0
	v_mov_b32_e32 v134, 0
	v_mov_b32_e32 v135, 0
	v_mov_b32_e32 v140, 0
	v_mov_b32_e32 v141, 0
	v_mov_b32_e32 v142, 0
	v_mov_b32_e32 v143, 0
	v_mov_b32_e32 v144, 0
	v_mov_b32_e32 v145, 0
	v_mov_b32_e32 v146, 0
	v_mov_b32_e32 v147, 0
	ds_read_b32 v148, v172 offset:0
	ds_read_b32 v149, v173 offset:0
	ds_read_b32 v150, v174 offset:0
	ds_read_b32 v151, v175 offset:0
	ds_read_b32 v152, v176 offset:0
	ds_read_b32 v153, v177 offset:0
	ds_read_b32 v154, v178 offset:0
	ds_read_b32 v155, v179 offset:0
	ds_read_b32 v156, v172 offset:124
	ds_read_b32 v157, v173 offset:124
	ds_read_b32 v158, v174 offset:124
	ds_read_b32 v159, v175 offset:124
	ds_read_b32 v160, v176 offset:124
	ds_read_b32 v161, v177 offset:124
	ds_read_b32 v162, v178 offset:124
	ds_read_b32 v163, v179 offset:124
	s_add_u32 s8, s6, 0
	s_lshl_b32 s8, s8, 6
	s_add_u32 s8, s8, s7
	s_lshl_b32 s8, s8, 1
	s_add_u32 s24, s18, s8
	s_addc_u32 s25, s19, 0
	global_load_dwordx4 v[44:47], v204, s[24:25]
	global_load_dwordx4 v[48:51], v205, s[24:25]
	global_load_dwordx4 v[52:55], v206, s[24:25]
	global_load_dwordx4 v[56:59], v207, s[24:25]
	s_add_u32 s8, s6, 1
	s_lshl_b32 s8, s8, 6
	s_add_u32 s8, s8, s7
	s_lshl_b32 s8, s8, 1
	s_add_u32 s24, s18, s8
	s_addc_u32 s25, s19, 0
	global_load_dwordx4 v[60:63], v204, s[24:25]
	global_load_dwordx4 v[64:67], v205, s[24:25]
	global_load_dwordx4 v[68:71], v206, s[24:25]
	global_load_dwordx4 v[72:75], v207, s[24:25]
	s_waitcnt vmcnt(8)
	v_mfma_f32_16x16x32_bf16 v[76:79], v[12:15], v[4:7], 0
	v_mfma_f32_16x16x32_bf16 v[76:79], v[16:19], v[8:11], v[76:79]
	v_mfma_f32_16x16x32_bf16 v[84:87], v[20:23], v[4:7], 0
	v_mfma_f32_16x16x32_bf16 v[84:87], v[24:27], v[8:11], v[84:87]
	v_mfma_f32_16x16x32_bf16 v[88:91], v[28:31], v[4:7], 0
	v_mfma_f32_16x16x32_bf16 v[88:91], v[32:35], v[8:11], v[88:91]
	v_mfma_f32_16x16x32_bf16 v[96:99], v[36:39], v[4:7], 0
	v_mfma_f32_16x16x32_bf16 v[96:99], v[40:43], v[8:11], v[96:99]
	s_add_u32 s8, s6, 2
	s_lshl_b32 s8, s8, 6
	s_add_u32 s8, s8, s7
	s_lshl_b32 s8, s8, 13
	s_add_u32 s22, s16, s8
	s_addc_u32 s23, s17, 0
	global_load_dwordx4 v[12:15], v208, s[22:23]
	global_load_dwordx4 v[16:19], v208, s[22:23] offset:64
	s_add_u32 s8, s6, 2
	s_lshl_b32 s8, s8, 6
	s_add_u32 s8, s8, s7
	s_lshl_b32 s8, s8, 13
	s_add_u32 s22, s16, s8
	s_addc_u32 s23, s17, 0
	global_load_dwordx4 v[20:23], v209, s[22:23]
	global_load_dwordx4 v[24:27], v209, s[22:23] offset:64
	s_add_u32 s8, s6, 3
	s_lshl_b32 s8, s8, 6
	s_add_u32 s8, s8, s7
	s_lshl_b32 s8, s8, 13
	s_add_u32 s22, s16, s8
	s_addc_u32 s23, s17, 0
	global_load_dwordx4 v[28:31], v208, s[22:23]
	global_load_dwordx4 v[32:35], v208, s[22:23] offset:64
	s_add_u32 s8, s6, 3
	s_lshl_b32 s8, s8, 6
	s_add_u32 s8, s8, s7
	s_lshl_b32 s8, s8, 13
	s_add_u32 s22, s16, s8
	s_addc_u32 s23, s17, 0
	global_load_dwordx4 v[36:39], v209, s[22:23]
	global_load_dwordx4 v[40:43], v209, s[22:23] offset:64
	s_nop 7
	s_waitcnt lgkmcnt(0)
	v_add_f32_e32 v148, v148, v180
	v_fma_f32 v76, v76, v214, v148
	v_add_f32_e32 v149, v149, v181
	v_fma_f32 v77, v77, v214, v149
	v_add_f32_e32 v150, v150, v182
	v_fma_f32 v78, v78, v214, v150
	v_add_f32_e32 v151, v151, v183
	v_fma_f32 v79, v79, v214, v151
	v_add_f32_e32 v152, v152, v184
	v_fma_f32 v84, v84, v214, v152
	v_add_f32_e32 v153, v153, v185
	v_fma_f32 v85, v85, v214, v153
	v_add_f32_e32 v154, v154, v186
	v_fma_f32 v86, v86, v214, v154
	v_add_f32_e32 v155, v155, v187
	v_fma_f32 v87, v87, v214, v155
	v_add_f32_e32 v156, v156, v180
	v_fma_f32 v88, v88, v214, v156
	v_add_f32_e32 v157, v157, v181
	v_fma_f32 v89, v89, v214, v157
	v_add_f32_e32 v158, v158, v182
	v_fma_f32 v90, v90, v214, v158
	v_add_f32_e32 v159, v159, v183
	v_fma_f32 v91, v91, v214, v159
	v_add_f32_e32 v160, v160, v184
	v_fma_f32 v96, v96, v214, v160
	v_add_f32_e32 v161, v161, v185
	v_fma_f32 v97, v97, v214, v161
	v_add_f32_e32 v162, v162, v186
	v_fma_f32 v98, v98, v214, v162
	v_add_f32_e32 v163, v163, v187
	v_fma_f32 v99, v99, v214, v163
	v_max3_f32 v126, v76, v77, v78
	v_max3_f32 v128, v79, v84, v85
	v_max3_f32 v126, v126, v86, v87
	v_max3_f32 v128, v128, v88, v89
	v_max3_f32 v126, v126, v90, v91
	v_max3_f32 v128, v128, v96, v97
	v_max3_f32 v126, v126, v98, v99
	v_max_f32_e32 v126, v126, v128
	v_mov_b32_e32 v128, v126
	s_nop 1
	v_permlane32_swap_b32_e32 v128, v126
	s_nop 1
	v_max_f32_e32 v126, v126, v128
	v_mov_b32_e32 v128, v126
	s_nop 1
	v_permlane16_swap_b32_e32 v128, v126
	s_nop 1
	v_max_f32_e32 v126, v126, v128
	v_max_f32_e32 v126, v80, v126
	v_sub_f32_e32 v124, v80, v126
	v_mov_b32_e32 v80, v126
	v_mul_f32_e32 v124, 0x3fb8aa3b, v124
	v_mul_f32_e32 v127, 0x3fb8aa3b, v126
	v_exp_f32_e32 v124, v124
	v_fma_f32 v76, v76, v215, -v127
	v_fma_f32 v77, v77, v215, -v127
	v_fma_f32 v78, v78, v215, -v127
	v_fma_f32 v79, v79, v215, -v127
	v_fma_f32 v84, v84, v215, -v127
	v_fma_f32 v85, v85, v215, -v127
	v_fma_f32 v86, v86, v215, -v127
	v_fma_f32 v87, v87, v215, -v127
	v_fma_f32 v88, v88, v215, -v127
	v_fma_f32 v89, v89, v215, -v127
	v_fma_f32 v90, v90, v215, -v127
	v_fma_f32 v91, v91, v215, -v127
	v_fma_f32 v96, v96, v215, -v127
	v_fma_f32 v97, v97, v215, -v127
	v_fma_f32 v98, v98, v215, -v127
	v_fma_f32 v99, v99, v215, -v127
	v_exp_f32_e32 v76, v76
	v_exp_f32_e32 v77, v77
	v_exp_f32_e32 v78, v78
	v_exp_f32_e32 v79, v79
	v_exp_f32_e32 v84, v84
	v_exp_f32_e32 v85, v85
	v_exp_f32_e32 v86, v86
	v_exp_f32_e32 v87, v87
	v_exp_f32_e32 v88, v88
	v_exp_f32_e32 v89, v89
	v_exp_f32_e32 v90, v90
	v_exp_f32_e32 v91, v91
	v_exp_f32_e32 v96, v96
	v_exp_f32_e32 v97, v97
	v_exp_f32_e32 v98, v98
	v_exp_f32_e32 v99, v99
	s_nop 0
	v_mul_f32_e32 v81, v81, v124
	v_add_f32_e32 v81, v81, v76
	v_add_f32_e32 v81, v81, v77
	v_add_f32_e32 v81, v81, v78
	v_add_f32_e32 v81, v81, v79
	v_add_f32_e32 v81, v81, v84
	v_add_f32_e32 v81, v81, v85
	v_add_f32_e32 v81, v81, v86
	v_add_f32_e32 v81, v81, v87
	v_add_f32_e32 v81, v81, v88
	v_add_f32_e32 v81, v81, v89
	v_add_f32_e32 v81, v81, v90
	v_add_f32_e32 v81, v81, v91
	v_add_f32_e32 v81, v81, v96
	v_add_f32_e32 v81, v81, v97
	v_add_f32_e32 v81, v81, v98
	v_add_f32_e32 v81, v81, v99
	v_cvt_pk_bf16_f32 v164, v76, v77
	v_cvt_pk_bf16_f32 v165, v78, v79
	v_cvt_pk_bf16_f32 v166, v84, v85
	v_cvt_pk_bf16_f32 v167, v86, v87
	v_cvt_pk_bf16_f32 v168, v88, v89
	v_cvt_pk_bf16_f32 v169, v90, v91
	v_cvt_pk_bf16_f32 v170, v96, v97
	v_cvt_pk_bf16_f32 v171, v98, v99
	v_mul_f32_e32 v100, v100, v124
	v_mul_f32_e32 v101, v101, v124
	v_mul_f32_e32 v102, v102, v124
	v_mul_f32_e32 v103, v103, v124
	v_mul_f32_e32 v132, v132, v124
	v_mul_f32_e32 v133, v133, v124
	v_mul_f32_e32 v134, v134, v124
	v_mul_f32_e32 v135, v135, v124
	v_mul_f32_e32 v140, v140, v124
	v_mul_f32_e32 v141, v141, v124
	v_mul_f32_e32 v142, v142, v124
	v_mul_f32_e32 v143, v143, v124
	v_mul_f32_e32 v144, v144, v124
	v_mul_f32_e32 v145, v145, v124
	v_mul_f32_e32 v146, v146, v124
	v_mul_f32_e32 v147, v147, v124
	s_waitcnt vmcnt(8)
	s_nop 1
	v_mfma_f32_16x16x32_bf16 v[100:103], v[44:47], v[164:167], v[100:103]
	v_mfma_f32_16x16x32_bf16 v[132:135], v[48:51], v[164:167], v[132:135]
	v_mfma_f32_16x16x32_bf16 v[140:143], v[52:55], v[164:167], v[140:143]
	v_mfma_f32_16x16x32_bf16 v[144:147], v[56:59], v[164:167], v[144:147]
	v_mfma_f32_16x16x32_bf16 v[100:103], v[60:63], v[168:171], v[100:103]
	v_mfma_f32_16x16x32_bf16 v[132:135], v[64:67], v[168:171], v[132:135]
	v_mfma_f32_16x16x32_bf16 v[140:143], v[68:71], v[168:171], v[140:143]
	v_mfma_f32_16x16x32_bf16 v[144:147], v[72:75], v[168:171], v[144:147]
	s_nop 3
	ds_read_b32 v148, v172 offset:248
	ds_read_b32 v149, v173 offset:248
	ds_read_b32 v150, v174 offset:248
	ds_read_b32 v151, v175 offset:248
	ds_read_b32 v152, v176 offset:248
	ds_read_b32 v153, v177 offset:248
	ds_read_b32 v154, v178 offset:248
	ds_read_b32 v155, v179 offset:248
	ds_read_b32 v156, v172 offset:372
	ds_read_b32 v157, v173 offset:372
	ds_read_b32 v158, v174 offset:372
	ds_read_b32 v159, v175 offset:372
	ds_read_b32 v160, v176 offset:372
	ds_read_b32 v161, v177 offset:372
	ds_read_b32 v162, v178 offset:372
	ds_read_b32 v163, v179 offset:372
	s_add_u32 s8, s6, 2
	s_lshl_b32 s8, s8, 6
	s_add_u32 s8, s8, s7
	s_lshl_b32 s8, s8, 1
	s_add_u32 s24, s18, s8
	s_addc_u32 s25, s19, 0
	global_load_dwordx4 v[44:47], v204, s[24:25]
	global_load_dwordx4 v[48:51], v205, s[24:25]
	global_load_dwordx4 v[52:55], v206, s[24:25]
	global_load_dwordx4 v[56:59], v207, s[24:25]
	s_add_u32 s8, s6, 3
	s_lshl_b32 s8, s8, 6
	s_add_u32 s8, s8, s7
	s_lshl_b32 s8, s8, 1
	s_add_u32 s24, s18, s8
	s_addc_u32 s25, s19, 0
	global_load_dwordx4 v[60:63], v204, s[24:25]
	global_load_dwordx4 v[64:67], v205, s[24:25]
	global_load_dwordx4 v[68:71], v206, s[24:25]
	global_load_dwordx4 v[72:75], v207, s[24:25]
	s_waitcnt vmcnt(8)
	v_mfma_f32_16x16x32_bf16 v[76:79], v[12:15], v[4:7], 0
	v_mfma_f32_16x16x32_bf16 v[76:79], v[16:19], v[8:11], v[76:79]
	v_mfma_f32_16x16x32_bf16 v[84:87], v[20:23], v[4:7], 0
	v_mfma_f32_16x16x32_bf16 v[84:87], v[24:27], v[8:11], v[84:87]
	v_mfma_f32_16x16x32_bf16 v[88:91], v[28:31], v[4:7], 0
	v_mfma_f32_16x16x32_bf16 v[88:91], v[32:35], v[8:11], v[88:91]
	v_mfma_f32_16x16x32_bf16 v[96:99], v[36:39], v[4:7], 0
	v_mfma_f32_16x16x32_bf16 v[96:99], v[40:43], v[8:11], v[96:99]
	s_add_u32 s8, s6, 4
	s_lshl_b32 s8, s8, 6
	s_add_u32 s8, s8, s7
	s_lshl_b32 s8, s8, 13
	s_add_u32 s22, s16, s8
	s_addc_u32 s23, s17, 0
	global_load_dwordx4 v[12:15], v208, s[22:23]
	global_load_dwordx4 v[16:19], v208, s[22:23] offset:64
	s_add_u32 s8, s6, 4
	s_lshl_b32 s8, s8, 6
	s_add_u32 s8, s8, s7
	s_lshl_b32 s8, s8, 13
	s_add_u32 s22, s16, s8
	s_addc_u32 s23, s17, 0
	global_load_dwordx4 v[20:23], v209, s[22:23]
	global_load_dwordx4 v[24:27], v209, s[22:23] offset:64
	s_add_u32 s8, s6, 5
	s_lshl_b32 s8, s8, 6
	s_add_u32 s8, s8, s7
	s_lshl_b32 s8, s8, 13
	s_add_u32 s22, s16, s8
	s_addc_u32 s23, s17, 0
	global_load_dwordx4 v[28:31], v208, s[22:23]
	global_load_dwordx4 v[32:35], v208, s[22:23] offset:64
	s_add_u32 s8, s6, 5
	s_lshl_b32 s8, s8, 6
	s_add_u32 s8, s8, s7
	s_lshl_b32 s8, s8, 13
	s_add_u32 s22, s16, s8
	s_addc_u32 s23, s17, 0
	global_load_dwordx4 v[36:39], v209, s[22:23]
	global_load_dwordx4 v[40:43], v209, s[22:23] offset:64
	s_nop 7
	s_waitcnt lgkmcnt(0)
	v_add_f32_e32 v148, v148, v180
	v_fma_f32 v76, v76, v214, v148
	v_add_f32_e32 v149, v149, v181
	v_fma_f32 v77, v77, v214, v149
	v_add_f32_e32 v150, v150, v182
	v_fma_f32 v78, v78, v214, v150
	v_add_f32_e32 v151, v151, v183
	v_fma_f32 v79, v79, v214, v151
	v_add_f32_e32 v152, v152, v184
	v_fma_f32 v84, v84, v214, v152
	v_add_f32_e32 v153, v153, v185
	v_fma_f32 v85, v85, v214, v153
	v_add_f32_e32 v154, v154, v186
	v_fma_f32 v86, v86, v214, v154
	v_add_f32_e32 v155, v155, v187
	v_fma_f32 v87, v87, v214, v155
	v_add_f32_e32 v156, v156, v180
	v_fma_f32 v88, v88, v214, v156
	v_add_f32_e32 v157, v157, v181
	v_fma_f32 v89, v89, v214, v157
	v_add_f32_e32 v158, v158, v182
	v_fma_f32 v90, v90, v214, v158
	v_add_f32_e32 v159, v159, v183
	v_fma_f32 v91, v91, v214, v159
	v_add_f32_e32 v160, v160, v184
	v_fma_f32 v96, v96, v214, v160
	v_add_f32_e32 v161, v161, v185
	v_fma_f32 v97, v97, v214, v161
	v_add_f32_e32 v162, v162, v186
	v_fma_f32 v98, v98, v214, v162
	v_add_f32_e32 v163, v163, v187
	v_fma_f32 v99, v99, v214, v163
	v_max3_f32 v126, v76, v77, v78
	v_max3_f32 v128, v79, v84, v85
	v_max3_f32 v126, v126, v86, v87
	v_max3_f32 v128, v128, v88, v89
	v_max3_f32 v126, v126, v90, v91
	v_max3_f32 v128, v128, v96, v97
	v_max3_f32 v126, v126, v98, v99
	v_max_f32_e32 v126, v126, v128
	v_mov_b32_e32 v128, v126
	s_nop 1
	v_permlane32_swap_b32_e32 v128, v126
	s_nop 1
	v_max_f32_e32 v126, v126, v128
	v_mov_b32_e32 v128, v126
	s_nop 1
	v_permlane16_swap_b32_e32 v128, v126
	s_nop 1
	v_max_f32_e32 v126, v126, v128
	v_max_f32_e32 v126, v80, v126
	v_sub_f32_e32 v124, v80, v126
	v_mov_b32_e32 v80, v126
	v_mul_f32_e32 v124, 0x3fb8aa3b, v124
	v_mul_f32_e32 v127, 0x3fb8aa3b, v126
	v_exp_f32_e32 v124, v124
	v_fma_f32 v76, v76, v215, -v127
	v_fma_f32 v77, v77, v215, -v127
	v_fma_f32 v78, v78, v215, -v127
	v_fma_f32 v79, v79, v215, -v127
	v_fma_f32 v84, v84, v215, -v127
	v_fma_f32 v85, v85, v215, -v127
	v_fma_f32 v86, v86, v215, -v127
	v_fma_f32 v87, v87, v215, -v127
	v_fma_f32 v88, v88, v215, -v127
	v_fma_f32 v89, v89, v215, -v127
	v_fma_f32 v90, v90, v215, -v127
	v_fma_f32 v91, v91, v215, -v127
	v_fma_f32 v96, v96, v215, -v127
	v_fma_f32 v97, v97, v215, -v127
	v_fma_f32 v98, v98, v215, -v127
	v_fma_f32 v99, v99, v215, -v127
	v_exp_f32_e32 v76, v76
	v_exp_f32_e32 v77, v77
	v_exp_f32_e32 v78, v78
	v_exp_f32_e32 v79, v79
	v_exp_f32_e32 v84, v84
	v_exp_f32_e32 v85, v85
	v_exp_f32_e32 v86, v86
	v_exp_f32_e32 v87, v87
	v_exp_f32_e32 v88, v88
	v_exp_f32_e32 v89, v89
	v_exp_f32_e32 v90, v90
	v_exp_f32_e32 v91, v91
	v_exp_f32_e32 v96, v96
	v_exp_f32_e32 v97, v97
	v_exp_f32_e32 v98, v98
	v_exp_f32_e32 v99, v99
	s_nop 0
	v_mul_f32_e32 v81, v81, v124
	v_add_f32_e32 v81, v81, v76
	v_add_f32_e32 v81, v81, v77
	v_add_f32_e32 v81, v81, v78
	v_add_f32_e32 v81, v81, v79
	v_add_f32_e32 v81, v81, v84
	v_add_f32_e32 v81, v81, v85
	v_add_f32_e32 v81, v81, v86
	v_add_f32_e32 v81, v81, v87
	v_add_f32_e32 v81, v81, v88
	v_add_f32_e32 v81, v81, v89
	v_add_f32_e32 v81, v81, v90
	v_add_f32_e32 v81, v81, v91
	v_add_f32_e32 v81, v81, v96
	v_add_f32_e32 v81, v81, v97
	v_add_f32_e32 v81, v81, v98
	v_add_f32_e32 v81, v81, v99
	v_cvt_pk_bf16_f32 v164, v76, v77
	v_cvt_pk_bf16_f32 v165, v78, v79
	v_cvt_pk_bf16_f32 v166, v84, v85
	v_cvt_pk_bf16_f32 v167, v86, v87
	v_cvt_pk_bf16_f32 v168, v88, v89
	v_cvt_pk_bf16_f32 v169, v90, v91
	v_cvt_pk_bf16_f32 v170, v96, v97
	v_cvt_pk_bf16_f32 v171, v98, v99
	v_mul_f32_e32 v100, v100, v124
	v_mul_f32_e32 v101, v101, v124
	v_mul_f32_e32 v102, v102, v124
	v_mul_f32_e32 v103, v103, v124
	v_mul_f32_e32 v132, v132, v124
	v_mul_f32_e32 v133, v133, v124
	v_mul_f32_e32 v134, v134, v124
	v_mul_f32_e32 v135, v135, v124
	v_mul_f32_e32 v140, v140, v124
	v_mul_f32_e32 v141, v141, v124
	v_mul_f32_e32 v142, v142, v124
	v_mul_f32_e32 v143, v143, v124
	v_mul_f32_e32 v144, v144, v124
	v_mul_f32_e32 v145, v145, v124
	v_mul_f32_e32 v146, v146, v124
	v_mul_f32_e32 v147, v147, v124
	s_waitcnt vmcnt(8)
	s_nop 1
	v_mfma_f32_16x16x32_bf16 v[100:103], v[44:47], v[164:167], v[100:103]
	v_mfma_f32_16x16x32_bf16 v[132:135], v[48:51], v[164:167], v[132:135]
	v_mfma_f32_16x16x32_bf16 v[140:143], v[52:55], v[164:167], v[140:143]
	v_mfma_f32_16x16x32_bf16 v[144:147], v[56:59], v[164:167], v[144:147]
	v_mfma_f32_16x16x32_bf16 v[100:103], v[60:63], v[168:171], v[100:103]
	v_mfma_f32_16x16x32_bf16 v[132:135], v[64:67], v[168:171], v[132:135]
	v_mfma_f32_16x16x32_bf16 v[140:143], v[68:71], v[168:171], v[140:143]
	v_mfma_f32_16x16x32_bf16 v[144:147], v[72:75], v[168:171], v[144:147]
	s_nop 3
	ds_read_b32 v148, v172 offset:496
	ds_read_b32 v149, v173 offset:496
	ds_read_b32 v150, v174 offset:496
	ds_read_b32 v151, v175 offset:496
	ds_read_b32 v152, v176 offset:496
	ds_read_b32 v153, v177 offset:496
	ds_read_b32 v154, v178 offset:496
	ds_read_b32 v155, v179 offset:496
	ds_read_b32 v156, v172 offset:620
	ds_read_b32 v157, v173 offset:620
	ds_read_b32 v158, v174 offset:620
	ds_read_b32 v159, v175 offset:620
	ds_read_b32 v160, v176 offset:620
	ds_read_b32 v161, v177 offset:620
	ds_read_b32 v162, v178 offset:620
	ds_read_b32 v163, v179 offset:620
	s_add_u32 s8, s6, 4
	s_lshl_b32 s8, s8, 6
	s_add_u32 s8, s8, s7
	s_lshl_b32 s8, s8, 1
	s_add_u32 s24, s18, s8
	s_addc_u32 s25, s19, 0
	global_load_dwordx4 v[44:47], v204, s[24:25]
	global_load_dwordx4 v[48:51], v205, s[24:25]
	global_load_dwordx4 v[52:55], v206, s[24:25]
	global_load_dwordx4 v[56:59], v207, s[24:25]
	s_add_u32 s8, s6, 5
	s_lshl_b32 s8, s8, 6
	s_add_u32 s8, s8, s7
	s_lshl_b32 s8, s8, 1
	s_add_u32 s24, s18, s8
	s_addc_u32 s25, s19, 0
	global_load_dwordx4 v[60:63], v204, s[24:25]
	global_load_dwordx4 v[64:67], v205, s[24:25]
	global_load_dwordx4 v[68:71], v206, s[24:25]
	global_load_dwordx4 v[72:75], v207, s[24:25]
	s_waitcnt vmcnt(8)
	v_mfma_f32_16x16x32_bf16 v[76:79], v[12:15], v[4:7], 0
	v_mfma_f32_16x16x32_bf16 v[76:79], v[16:19], v[8:11], v[76:79]
	v_mfma_f32_16x16x32_bf16 v[84:87], v[20:23], v[4:7], 0
	v_mfma_f32_16x16x32_bf16 v[84:87], v[24:27], v[8:11], v[84:87]
	v_mfma_f32_16x16x32_bf16 v[88:91], v[28:31], v[4:7], 0
	v_mfma_f32_16x16x32_bf16 v[88:91], v[32:35], v[8:11], v[88:91]
	v_mfma_f32_16x16x32_bf16 v[96:99], v[36:39], v[4:7], 0
	v_mfma_f32_16x16x32_bf16 v[96:99], v[40:43], v[8:11], v[96:99]
	s_add_u32 s8, s6, 6
	s_lshl_b32 s8, s8, 6
	s_add_u32 s8, s8, s7
	s_lshl_b32 s8, s8, 13
	s_add_u32 s22, s16, s8
	s_addc_u32 s23, s17, 0
	global_load_dwordx4 v[12:15], v208, s[22:23]
	global_load_dwordx4 v[16:19], v208, s[22:23] offset:64
	s_add_u32 s8, s6, 6
	s_lshl_b32 s8, s8, 6
	s_add_u32 s8, s8, s7
	s_lshl_b32 s8, s8, 13
	s_add_u32 s22, s16, s8
	s_addc_u32 s23, s17, 0
	global_load_dwordx4 v[20:23], v209, s[22:23]
	global_load_dwordx4 v[24:27], v209, s[22:23] offset:64
	s_add_u32 s8, s6, 7
	s_lshl_b32 s8, s8, 6
	s_add_u32 s8, s8, s7
	s_lshl_b32 s8, s8, 13
	s_add_u32 s22, s16, s8
	s_addc_u32 s23, s17, 0
	global_load_dwordx4 v[28:31], v208, s[22:23]
	global_load_dwordx4 v[32:35], v208, s[22:23] offset:64
	s_add_u32 s8, s6, 7
	s_lshl_b32 s8, s8, 6
	s_add_u32 s8, s8, s7
	s_lshl_b32 s8, s8, 13
	s_add_u32 s22, s16, s8
	s_addc_u32 s23, s17, 0
	global_load_dwordx4 v[36:39], v209, s[22:23]
	global_load_dwordx4 v[40:43], v209, s[22:23] offset:64
	s_nop 7
	s_waitcnt lgkmcnt(0)
	v_add_f32_e32 v148, v148, v180
	v_fma_f32 v76, v76, v214, v148
	v_add_f32_e32 v149, v149, v181
	v_fma_f32 v77, v77, v214, v149
	v_add_f32_e32 v150, v150, v182
	v_fma_f32 v78, v78, v214, v150
	v_add_f32_e32 v151, v151, v183
	v_fma_f32 v79, v79, v214, v151
	v_add_f32_e32 v152, v152, v184
	v_fma_f32 v84, v84, v214, v152
	v_add_f32_e32 v153, v153, v185
	v_fma_f32 v85, v85, v214, v153
	v_add_f32_e32 v154, v154, v186
	v_fma_f32 v86, v86, v214, v154
	v_add_f32_e32 v155, v155, v187
	v_fma_f32 v87, v87, v214, v155
	v_add_f32_e32 v156, v156, v180
	v_fma_f32 v88, v88, v214, v156
	v_add_f32_e32 v157, v157, v181
	v_fma_f32 v89, v89, v214, v157
	v_add_f32_e32 v158, v158, v182
	v_fma_f32 v90, v90, v214, v158
	v_add_f32_e32 v159, v159, v183
	v_fma_f32 v91, v91, v214, v159
	v_add_f32_e32 v160, v160, v184
	v_fma_f32 v96, v96, v214, v160
	v_add_f32_e32 v161, v161, v185
	v_fma_f32 v97, v97, v214, v161
	v_add_f32_e32 v162, v162, v186
	v_fma_f32 v98, v98, v214, v162
	v_add_f32_e32 v163, v163, v187
	v_fma_f32 v99, v99, v214, v163
	v_max3_f32 v126, v76, v77, v78
	v_max3_f32 v128, v79, v84, v85
	v_max3_f32 v126, v126, v86, v87
	v_max3_f32 v128, v128, v88, v89
	v_max3_f32 v126, v126, v90, v91
	v_max3_f32 v128, v128, v96, v97
	v_max3_f32 v126, v126, v98, v99
	v_max_f32_e32 v126, v126, v128
	v_mov_b32_e32 v128, v126
	s_nop 1
	v_permlane32_swap_b32_e32 v128, v126
	s_nop 1
	v_max_f32_e32 v126, v126, v128
	v_mov_b32_e32 v128, v126
	s_nop 1
	v_permlane16_swap_b32_e32 v128, v126
	s_nop 1
	v_max_f32_e32 v126, v126, v128
	v_max_f32_e32 v126, v80, v126
	v_sub_f32_e32 v124, v80, v126
	v_mov_b32_e32 v80, v126
	v_mul_f32_e32 v124, 0x3fb8aa3b, v124
	v_mul_f32_e32 v127, 0x3fb8aa3b, v126
	v_exp_f32_e32 v124, v124
	v_fma_f32 v76, v76, v215, -v127
	v_fma_f32 v77, v77, v215, -v127
	v_fma_f32 v78, v78, v215, -v127
	v_fma_f32 v79, v79, v215, -v127
	v_fma_f32 v84, v84, v215, -v127
	v_fma_f32 v85, v85, v215, -v127
	v_fma_f32 v86, v86, v215, -v127
	v_fma_f32 v87, v87, v215, -v127
	v_fma_f32 v88, v88, v215, -v127
	v_fma_f32 v89, v89, v215, -v127
	v_fma_f32 v90, v90, v215, -v127
	v_fma_f32 v91, v91, v215, -v127
	v_fma_f32 v96, v96, v215, -v127
	v_fma_f32 v97, v97, v215, -v127
	v_fma_f32 v98, v98, v215, -v127
	v_fma_f32 v99, v99, v215, -v127
	v_exp_f32_e32 v76, v76
	v_exp_f32_e32 v77, v77
	v_exp_f32_e32 v78, v78
	v_exp_f32_e32 v79, v79
	v_exp_f32_e32 v84, v84
	v_exp_f32_e32 v85, v85
	v_exp_f32_e32 v86, v86
	v_exp_f32_e32 v87, v87
	v_exp_f32_e32 v88, v88
	v_exp_f32_e32 v89, v89
	v_exp_f32_e32 v90, v90
	v_exp_f32_e32 v91, v91
	v_exp_f32_e32 v96, v96
	v_exp_f32_e32 v97, v97
	v_exp_f32_e32 v98, v98
	v_exp_f32_e32 v99, v99
	s_nop 0
	v_mul_f32_e32 v81, v81, v124
	v_add_f32_e32 v81, v81, v76
	v_add_f32_e32 v81, v81, v77
	v_add_f32_e32 v81, v81, v78
	v_add_f32_e32 v81, v81, v79
	v_add_f32_e32 v81, v81, v84
	v_add_f32_e32 v81, v81, v85
	v_add_f32_e32 v81, v81, v86
	v_add_f32_e32 v81, v81, v87
	v_add_f32_e32 v81, v81, v88
	v_add_f32_e32 v81, v81, v89
	v_add_f32_e32 v81, v81, v90
	v_add_f32_e32 v81, v81, v91
	v_add_f32_e32 v81, v81, v96
	v_add_f32_e32 v81, v81, v97
	v_add_f32_e32 v81, v81, v98
	v_add_f32_e32 v81, v81, v99
	v_cvt_pk_bf16_f32 v164, v76, v77
	v_cvt_pk_bf16_f32 v165, v78, v79
	v_cvt_pk_bf16_f32 v166, v84, v85
	v_cvt_pk_bf16_f32 v167, v86, v87
	v_cvt_pk_bf16_f32 v168, v88, v89
	v_cvt_pk_bf16_f32 v169, v90, v91
	v_cvt_pk_bf16_f32 v170, v96, v97
	v_cvt_pk_bf16_f32 v171, v98, v99
	v_mul_f32_e32 v100, v100, v124
	v_mul_f32_e32 v101, v101, v124
	v_mul_f32_e32 v102, v102, v124
	v_mul_f32_e32 v103, v103, v124
	v_mul_f32_e32 v132, v132, v124
	v_mul_f32_e32 v133, v133, v124
	v_mul_f32_e32 v134, v134, v124
	v_mul_f32_e32 v135, v135, v124
	v_mul_f32_e32 v140, v140, v124
	v_mul_f32_e32 v141, v141, v124
	v_mul_f32_e32 v142, v142, v124
	v_mul_f32_e32 v143, v143, v124
	v_mul_f32_e32 v144, v144, v124
	v_mul_f32_e32 v145, v145, v124
	v_mul_f32_e32 v146, v146, v124
	v_mul_f32_e32 v147, v147, v124
	s_waitcnt vmcnt(8)
	s_nop 1
	v_mfma_f32_16x16x32_bf16 v[100:103], v[44:47], v[164:167], v[100:103]
	v_mfma_f32_16x16x32_bf16 v[132:135], v[48:51], v[164:167], v[132:135]
	v_mfma_f32_16x16x32_bf16 v[140:143], v[52:55], v[164:167], v[140:143]
	v_mfma_f32_16x16x32_bf16 v[144:147], v[56:59], v[164:167], v[144:147]
	v_mfma_f32_16x16x32_bf16 v[100:103], v[60:63], v[168:171], v[100:103]
	v_mfma_f32_16x16x32_bf16 v[132:135], v[64:67], v[168:171], v[132:135]
	v_mfma_f32_16x16x32_bf16 v[140:143], v[68:71], v[168:171], v[140:143]
	v_mfma_f32_16x16x32_bf16 v[144:147], v[72:75], v[168:171], v[144:147]
	s_nop 3
	ds_read_b32 v148, v172 offset:744
	ds_read_b32 v149, v173 offset:744
	ds_read_b32 v150, v174 offset:744
	ds_read_b32 v151, v175 offset:744
	ds_read_b32 v152, v176 offset:744
	ds_read_b32 v153, v177 offset:744
	ds_read_b32 v154, v178 offset:744
	ds_read_b32 v155, v179 offset:744
	ds_read_b32 v156, v172 offset:868
	ds_read_b32 v157, v173 offset:868
	ds_read_b32 v158, v174 offset:868
	ds_read_b32 v159, v175 offset:868
	ds_read_b32 v160, v176 offset:868
	ds_read_b32 v161, v177 offset:868
	ds_read_b32 v162, v178 offset:868
	ds_read_b32 v163, v179 offset:868
	s_add_u32 s8, s6, 6
	s_lshl_b32 s8, s8, 6
	s_add_u32 s8, s8, s7
	s_lshl_b32 s8, s8, 1
	s_add_u32 s24, s18, s8
	s_addc_u32 s25, s19, 0
	global_load_dwordx4 v[44:47], v204, s[24:25]
	global_load_dwordx4 v[48:51], v205, s[24:25]
	global_load_dwordx4 v[52:55], v206, s[24:25]
	global_load_dwordx4 v[56:59], v207, s[24:25]
	s_add_u32 s8, s6, 7
	s_lshl_b32 s8, s8, 6
	s_add_u32 s8, s8, s7
	s_lshl_b32 s8, s8, 1
	s_add_u32 s24, s18, s8
	s_addc_u32 s25, s19, 0
	global_load_dwordx4 v[60:63], v204, s[24:25]
	global_load_dwordx4 v[64:67], v205, s[24:25]
	global_load_dwordx4 v[68:71], v206, s[24:25]
	global_load_dwordx4 v[72:75], v207, s[24:25]
	s_waitcnt vmcnt(8)
	v_mfma_f32_16x16x32_bf16 v[76:79], v[12:15], v[4:7], 0
	v_mfma_f32_16x16x32_bf16 v[76:79], v[16:19], v[8:11], v[76:79]
	v_mfma_f32_16x16x32_bf16 v[84:87], v[20:23], v[4:7], 0
	v_mfma_f32_16x16x32_bf16 v[84:87], v[24:27], v[8:11], v[84:87]
	v_mfma_f32_16x16x32_bf16 v[88:91], v[28:31], v[4:7], 0
	v_mfma_f32_16x16x32_bf16 v[88:91], v[32:35], v[8:11], v[88:91]
	v_mfma_f32_16x16x32_bf16 v[96:99], v[36:39], v[4:7], 0
	v_mfma_f32_16x16x32_bf16 v[96:99], v[40:43], v[8:11], v[96:99]
	ds_read_b128 v[12:15], v210 offset:0
	ds_read_b128 v[16:19], v210 offset:64
	ds_read_b128 v[20:23], v211 offset:0
	ds_read_b128 v[24:27], v211 offset:64
	ds_read_b128 v[28:31], v210 offset:4608
	ds_read_b128 v[32:35], v210 offset:4672
	ds_read_b128 v[36:39], v211 offset:4608
	ds_read_b128 v[40:43], v211 offset:4672
	s_nop 7
	s_waitcnt lgkmcnt(8)
	v_add_f32_e32 v148, v148, v180
	v_fma_f32 v76, v76, v214, v148
	v_add_f32_e32 v149, v149, v181
	v_fma_f32 v77, v77, v214, v149
	v_add_f32_e32 v150, v150, v182
	v_fma_f32 v78, v78, v214, v150
	v_add_f32_e32 v151, v151, v183
	v_fma_f32 v79, v79, v214, v151
	v_add_f32_e32 v152, v152, v184
	v_fma_f32 v84, v84, v214, v152
	v_add_f32_e32 v153, v153, v185
	v_fma_f32 v85, v85, v214, v153
	v_add_f32_e32 v154, v154, v186
	v_fma_f32 v86, v86, v214, v154
	v_add_f32_e32 v155, v155, v187
	v_fma_f32 v87, v87, v214, v155
	v_add_f32_e32 v156, v156, v180
	v_fma_f32 v88, v88, v214, v156
	v_add_f32_e32 v157, v157, v181
	v_fma_f32 v89, v89, v214, v157
	v_add_f32_e32 v158, v158, v182
	v_fma_f32 v90, v90, v214, v158
	v_add_f32_e32 v159, v159, v183
	v_fma_f32 v91, v91, v214, v159
	v_add_f32_e32 v160, v160, v184
	v_fma_f32 v96, v96, v214, v160
	v_add_f32_e32 v161, v161, v185
	v_fma_f32 v97, v97, v214, v161
	v_add_f32_e32 v162, v162, v186
	v_fma_f32 v98, v98, v214, v162
	v_add_f32_e32 v163, v163, v187
	v_fma_f32 v99, v99, v214, v163
	v_max3_f32 v126, v76, v77, v78
	v_max3_f32 v128, v79, v84, v85
	v_max3_f32 v126, v126, v86, v87
	v_max3_f32 v128, v128, v88, v89
	v_max3_f32 v126, v126, v90, v91
	v_max3_f32 v128, v128, v96, v97
	v_max3_f32 v126, v126, v98, v99
	v_max_f32_e32 v126, v126, v128
	v_mov_b32_e32 v128, v126
	s_nop 1
	v_permlane32_swap_b32_e32 v128, v126
	s_nop 1
	v_max_f32_e32 v126, v126, v128
	v_mov_b32_e32 v128, v126
	s_nop 1
	v_permlane16_swap_b32_e32 v128, v126
	s_nop 1
	v_max_f32_e32 v126, v126, v128
	v_max_f32_e32 v126, v80, v126
	v_sub_f32_e32 v124, v80, v126
	v_mov_b32_e32 v80, v126
	v_mul_f32_e32 v124, 0x3fb8aa3b, v124
	v_mul_f32_e32 v127, 0x3fb8aa3b, v126
	v_exp_f32_e32 v124, v124
	v_fma_f32 v76, v76, v215, -v127
	v_fma_f32 v77, v77, v215, -v127
	v_fma_f32 v78, v78, v215, -v127
	v_fma_f32 v79, v79, v215, -v127
	v_fma_f32 v84, v84, v215, -v127
	v_fma_f32 v85, v85, v215, -v127
	v_fma_f32 v86, v86, v215, -v127
	v_fma_f32 v87, v87, v215, -v127
	v_fma_f32 v88, v88, v215, -v127
	v_fma_f32 v89, v89, v215, -v127
	v_fma_f32 v90, v90, v215, -v127
	v_fma_f32 v91, v91, v215, -v127
	v_fma_f32 v96, v96, v215, -v127
	v_fma_f32 v97, v97, v215, -v127
	v_fma_f32 v98, v98, v215, -v127
	v_fma_f32 v99, v99, v215, -v127
	v_exp_f32_e32 v76, v76
	v_exp_f32_e32 v77, v77
	v_exp_f32_e32 v78, v78
	v_exp_f32_e32 v79, v79
	v_exp_f32_e32 v84, v84
	v_exp_f32_e32 v85, v85
	v_exp_f32_e32 v86, v86
	v_exp_f32_e32 v87, v87
	v_exp_f32_e32 v88, v88
	v_exp_f32_e32 v89, v89
	v_exp_f32_e32 v90, v90
	v_exp_f32_e32 v91, v91
	v_exp_f32_e32 v96, v96
	v_exp_f32_e32 v97, v97
	v_exp_f32_e32 v98, v98
	v_exp_f32_e32 v99, v99
	s_nop 0
	v_mul_f32_e32 v81, v81, v124
	v_add_f32_e32 v81, v81, v76
	v_add_f32_e32 v81, v81, v77
	v_add_f32_e32 v81, v81, v78
	v_add_f32_e32 v81, v81, v79
	v_add_f32_e32 v81, v81, v84
	v_add_f32_e32 v81, v81, v85
	v_add_f32_e32 v81, v81, v86
	v_add_f32_e32 v81, v81, v87
	v_add_f32_e32 v81, v81, v88
	v_add_f32_e32 v81, v81, v89
	v_add_f32_e32 v81, v81, v90
	v_add_f32_e32 v81, v81, v91
	v_add_f32_e32 v81, v81, v96
	v_add_f32_e32 v81, v81, v97
	v_add_f32_e32 v81, v81, v98
	v_add_f32_e32 v81, v81, v99
	v_cvt_pk_bf16_f32 v164, v76, v77
	v_cvt_pk_bf16_f32 v165, v78, v79
	v_cvt_pk_bf16_f32 v166, v84, v85
	v_cvt_pk_bf16_f32 v167, v86, v87
	v_cvt_pk_bf16_f32 v168, v88, v89
	v_cvt_pk_bf16_f32 v169, v90, v91
	v_cvt_pk_bf16_f32 v170, v96, v97
	v_cvt_pk_bf16_f32 v171, v98, v99
	v_mul_f32_e32 v100, v100, v124
	v_mul_f32_e32 v101, v101, v124
	v_mul_f32_e32 v102, v102, v124
	v_mul_f32_e32 v103, v103, v124
	v_mul_f32_e32 v132, v132, v124
	v_mul_f32_e32 v133, v133, v124
	v_mul_f32_e32 v134, v134, v124
	v_mul_f32_e32 v135, v135, v124
	v_mul_f32_e32 v140, v140, v124
	v_mul_f32_e32 v141, v141, v124
	v_mul_f32_e32 v142, v142, v124
	v_mul_f32_e32 v143, v143, v124
	v_mul_f32_e32 v144, v144, v124
	v_mul_f32_e32 v145, v145, v124
	v_mul_f32_e32 v146, v146, v124
	v_mul_f32_e32 v147, v147, v124
	s_waitcnt vmcnt(0)
	s_nop 1
	v_mfma_f32_16x16x32_bf16 v[100:103], v[44:47], v[164:167], v[100:103]
	v_mfma_f32_16x16x32_bf16 v[132:135], v[48:51], v[164:167], v[132:135]
	v_mfma_f32_16x16x32_bf16 v[140:143], v[52:55], v[164:167], v[140:143]
	v_mfma_f32_16x16x32_bf16 v[144:147], v[56:59], v[164:167], v[144:147]
	v_mfma_f32_16x16x32_bf16 v[100:103], v[60:63], v[168:171], v[100:103]
	v_mfma_f32_16x16x32_bf16 v[132:135], v[64:67], v[168:171], v[132:135]
	v_mfma_f32_16x16x32_bf16 v[140:143], v[68:71], v[168:171], v[140:143]
	v_mfma_f32_16x16x32_bf16 v[144:147], v[72:75], v[168:171], v[144:147]
	s_nop 3
	ds_read_b128 v[44:47], v195 offset:0
	ds_read_b128 v[48:51], v195 offset:8448
	ds_read_b128 v[52:55], v195 offset:16896
	ds_read_b128 v[56:59], v195 offset:25344
	ds_read_b128 v[60:63], v195 offset:64
	ds_read_b128 v[64:67], v195 offset:8512
	ds_read_b128 v[68:71], v195 offset:16960
	ds_read_b128 v[72:75], v195 offset:25408
	s_waitcnt vmcnt(0)
	s_nop 0
	s_waitcnt lgkmcnt(15)
	s_waitcnt lgkmcnt(0)
	v_mfma_f32_16x16x32_bf16 v[76:79], v[12:15], v[4:7], 0
	v_mfma_f32_16x16x32_bf16 v[76:79], v[16:19], v[8:11], v[76:79]
	v_mfma_f32_16x16x32_bf16 v[84:87], v[20:23], v[4:7], 0
	v_mfma_f32_16x16x32_bf16 v[84:87], v[24:27], v[8:11], v[84:87]
	v_mfma_f32_16x16x32_bf16 v[88:91], v[28:31], v[4:7], 0
	v_mfma_f32_16x16x32_bf16 v[88:91], v[32:35], v[8:11], v[88:91]
	v_mfma_f32_16x16x32_bf16 v[96:99], v[36:39], v[4:7], 0
	v_mfma_f32_16x16x32_bf16 v[96:99], v[40:43], v[8:11], v[96:99]
	ds_read_b128 v[12:15], v210 offset:9216
	ds_read_b128 v[16:19], v210 offset:9280
	ds_read_b128 v[20:23], v211 offset:9216
	ds_read_b128 v[24:27], v211 offset:9280
	ds_read_b128 v[28:31], v210 offset:13824
	ds_read_b128 v[32:35], v210 offset:13888
	ds_read_b128 v[36:39], v211 offset:13824
	ds_read_b128 v[40:43], v211 offset:13888
	s_nop 7
	v_mul_f32_e32 v76, 0x3e000000, v76
	v_mul_f32_e32 v77, 0x3e000000, v77
	v_mul_f32_e32 v78, 0x3e000000, v78
	v_mul_f32_e32 v79, 0x3e000000, v79
	v_mul_f32_e32 v84, 0x3e000000, v84
	v_mul_f32_e32 v85, 0x3e000000, v85
	v_mul_f32_e32 v86, 0x3e000000, v86
	v_mul_f32_e32 v87, 0x3e000000, v87
	v_mul_f32_e32 v88, 0x3e000000, v88
	v_mul_f32_e32 v89, 0x3e000000, v89
	v_mul_f32_e32 v90, 0x3e000000, v90
	v_mul_f32_e32 v91, 0x3e000000, v91
	v_mul_f32_e32 v96, 0x3e000000, v96
	v_mul_f32_e32 v97, 0x3e000000, v97
	v_mul_f32_e32 v98, 0x3e000000, v98
	v_mul_f32_e32 v99, 0x3e000000, v99
	v_max3_f32 v126, v76, v77, v78
	v_max3_f32 v128, v79, v84, v85
	v_max3_f32 v126, v126, v86, v87
	v_max3_f32 v128, v128, v88, v89
	v_max3_f32 v126, v126, v90, v91
	v_max3_f32 v128, v128, v96, v97
	v_max3_f32 v126, v126, v98, v99
	v_max_f32_e32 v126, v126, v128
	v_mov_b32_e32 v128, v126
	s_nop 1
	v_permlane32_swap_b32_e32 v128, v126
	s_nop 1
	v_max_f32_e32 v126, v126, v128
	v_mov_b32_e32 v128, v126
	s_nop 1
	v_permlane16_swap_b32_e32 v128, v126
	s_nop 1
	v_max_f32_e32 v126, v126, v128
	v_max_f32_e32 v126, v80, v126
	v_sub_f32_e32 v124, v80, v126
	v_mov_b32_e32 v80, v126
	v_mul_f32_e32 v124, 0x3fb8aa3b, v124
	v_mul_f32_e32 v127, 0x3fb8aa3b, v126
	v_exp_f32_e32 v124, v124
	v_fma_f32 v76, v76, v215, -v127
	v_fma_f32 v77, v77, v215, -v127
	v_fma_f32 v78, v78, v215, -v127
	v_fma_f32 v79, v79, v215, -v127
	v_fma_f32 v84, v84, v215, -v127
	v_fma_f32 v85, v85, v215, -v127
	v_fma_f32 v86, v86, v215, -v127
	v_fma_f32 v87, v87, v215, -v127
	v_fma_f32 v88, v88, v215, -v127
	v_fma_f32 v89, v89, v215, -v127
	v_fma_f32 v90, v90, v215, -v127
	v_fma_f32 v91, v91, v215, -v127
	v_fma_f32 v96, v96, v215, -v127
	v_fma_f32 v97, v97, v215, -v127
	v_fma_f32 v98, v98, v215, -v127
	v_fma_f32 v99, v99, v215, -v127
	v_exp_f32_e32 v76, v76
	v_exp_f32_e32 v77, v77
	v_exp_f32_e32 v78, v78
	v_exp_f32_e32 v79, v79
	v_exp_f32_e32 v84, v84
	v_exp_f32_e32 v85, v85
	v_exp_f32_e32 v86, v86
	v_exp_f32_e32 v87, v87
	v_exp_f32_e32 v88, v88
	v_exp_f32_e32 v89, v89
	v_exp_f32_e32 v90, v90
	v_exp_f32_e32 v91, v91
	v_exp_f32_e32 v96, v96
	v_exp_f32_e32 v97, v97
	v_exp_f32_e32 v98, v98
	v_exp_f32_e32 v99, v99
	s_nop 0
	v_mul_f32_e32 v81, v81, v124
	v_add_f32_e32 v81, v81, v76
	v_add_f32_e32 v81, v81, v77
	v_add_f32_e32 v81, v81, v78
	v_add_f32_e32 v81, v81, v79
	v_add_f32_e32 v81, v81, v84
	v_add_f32_e32 v81, v81, v85
	v_add_f32_e32 v81, v81, v86
	v_add_f32_e32 v81, v81, v87
	v_add_f32_e32 v81, v81, v88
	v_add_f32_e32 v81, v81, v89
	v_add_f32_e32 v81, v81, v90
	v_add_f32_e32 v81, v81, v91
	v_add_f32_e32 v81, v81, v96
	v_add_f32_e32 v81, v81, v97
	v_add_f32_e32 v81, v81, v98
	v_add_f32_e32 v81, v81, v99
	v_cvt_pk_bf16_f32 v164, v76, v77
	v_cvt_pk_bf16_f32 v165, v78, v79
	v_cvt_pk_bf16_f32 v166, v84, v85
	v_cvt_pk_bf16_f32 v167, v86, v87
	v_cvt_pk_bf16_f32 v168, v88, v89
	v_cvt_pk_bf16_f32 v169, v90, v91
	v_cvt_pk_bf16_f32 v170, v96, v97
	v_cvt_pk_bf16_f32 v171, v98, v99
	v_mul_f32_e32 v100, v100, v124
	v_mul_f32_e32 v101, v101, v124
	v_mul_f32_e32 v102, v102, v124
	v_mul_f32_e32 v103, v103, v124
	v_mul_f32_e32 v132, v132, v124
	v_mul_f32_e32 v133, v133, v124
	v_mul_f32_e32 v134, v134, v124
	v_mul_f32_e32 v135, v135, v124
	v_mul_f32_e32 v140, v140, v124
	v_mul_f32_e32 v141, v141, v124
	v_mul_f32_e32 v142, v142, v124
	v_mul_f32_e32 v143, v143, v124
	v_mul_f32_e32 v144, v144, v124
	v_mul_f32_e32 v145, v145, v124
	v_mul_f32_e32 v146, v146, v124
	v_mul_f32_e32 v147, v147, v124
	s_waitcnt lgkmcnt(8)
	s_nop 1
	v_mfma_f32_16x16x32_bf16 v[100:103], v[44:47], v[164:167], v[100:103]
	v_mfma_f32_16x16x32_bf16 v[132:135], v[48:51], v[164:167], v[132:135]
	v_mfma_f32_16x16x32_bf16 v[140:143], v[52:55], v[164:167], v[140:143]
	v_mfma_f32_16x16x32_bf16 v[144:147], v[56:59], v[164:167], v[144:147]
	v_mfma_f32_16x16x32_bf16 v[100:103], v[60:63], v[168:171], v[100:103]
	v_mfma_f32_16x16x32_bf16 v[132:135], v[64:67], v[168:171], v[132:135]
	v_mfma_f32_16x16x32_bf16 v[140:143], v[68:71], v[168:171], v[140:143]
	v_mfma_f32_16x16x32_bf16 v[144:147], v[72:75], v[168:171], v[144:147]
	s_nop 3
	ds_read_b128 v[44:47], v195 offset:128
	ds_read_b128 v[48:51], v195 offset:8576
	ds_read_b128 v[52:55], v195 offset:17024
	ds_read_b128 v[56:59], v195 offset:25472
	ds_read_b128 v[60:63], v195 offset:192
	ds_read_b128 v[64:67], v195 offset:8640
	ds_read_b128 v[68:71], v195 offset:17088
	ds_read_b128 v[72:75], v195 offset:25536
	s_nop 0
	s_nop 0
	s_waitcnt lgkmcnt(15)
	s_waitcnt lgkmcnt(0)
	v_mfma_f32_16x16x32_bf16 v[76:79], v[12:15], v[4:7], 0
	v_mfma_f32_16x16x32_bf16 v[76:79], v[16:19], v[8:11], v[76:79]
	v_mfma_f32_16x16x32_bf16 v[84:87], v[20:23], v[4:7], 0
	v_mfma_f32_16x16x32_bf16 v[84:87], v[24:27], v[8:11], v[84:87]
	v_mfma_f32_16x16x32_bf16 v[88:91], v[28:31], v[4:7], 0
	v_mfma_f32_16x16x32_bf16 v[88:91], v[32:35], v[8:11], v[88:91]
	v_mfma_f32_16x16x32_bf16 v[96:99], v[36:39], v[4:7], 0
	v_mfma_f32_16x16x32_bf16 v[96:99], v[40:43], v[8:11], v[96:99]
	ds_read_b128 v[12:15], v210 offset:18432
	ds_read_b128 v[16:19], v210 offset:18496
	ds_read_b128 v[20:23], v211 offset:18432
	ds_read_b128 v[24:27], v211 offset:18496
	ds_read_b128 v[28:31], v210 offset:23040
	ds_read_b128 v[32:35], v210 offset:23104
	ds_read_b128 v[36:39], v211 offset:23040
	ds_read_b128 v[40:43], v211 offset:23104
	s_nop 7
	v_mul_f32_e32 v76, 0x3e000000, v76
	v_mul_f32_e32 v77, 0x3e000000, v77
	v_mul_f32_e32 v78, 0x3e000000, v78
	v_mul_f32_e32 v79, 0x3e000000, v79
	v_mul_f32_e32 v84, 0x3e000000, v84
	v_mul_f32_e32 v85, 0x3e000000, v85
	v_mul_f32_e32 v86, 0x3e000000, v86
	v_mul_f32_e32 v87, 0x3e000000, v87
	v_mul_f32_e32 v88, 0x3e000000, v88
	v_mul_f32_e32 v89, 0x3e000000, v89
	v_mul_f32_e32 v90, 0x3e000000, v90
	v_mul_f32_e32 v91, 0x3e000000, v91
	v_mul_f32_e32 v96, 0x3e000000, v96
	v_mul_f32_e32 v97, 0x3e000000, v97
	v_mul_f32_e32 v98, 0x3e000000, v98
	v_mul_f32_e32 v99, 0x3e000000, v99
	v_max3_f32 v126, v76, v77, v78
	v_max3_f32 v128, v79, v84, v85
	v_max3_f32 v126, v126, v86, v87
	v_max3_f32 v128, v128, v88, v89
	v_max3_f32 v126, v126, v90, v91
	v_max3_f32 v128, v128, v96, v97
	v_max3_f32 v126, v126, v98, v99
	v_max_f32_e32 v126, v126, v128
	v_mov_b32_e32 v128, v126
	s_nop 1
	v_permlane32_swap_b32_e32 v128, v126
	s_nop 1
	v_max_f32_e32 v126, v126, v128
	v_mov_b32_e32 v128, v126
	s_nop 1
	v_permlane16_swap_b32_e32 v128, v126
	s_nop 1
	v_max_f32_e32 v126, v126, v128
	v_max_f32_e32 v126, v80, v126
	v_sub_f32_e32 v124, v80, v126
	v_mov_b32_e32 v80, v126
	v_mul_f32_e32 v124, 0x3fb8aa3b, v124
	v_mul_f32_e32 v127, 0x3fb8aa3b, v126
	v_exp_f32_e32 v124, v124
	v_fma_f32 v76, v76, v215, -v127
	v_fma_f32 v77, v77, v215, -v127
	v_fma_f32 v78, v78, v215, -v127
	v_fma_f32 v79, v79, v215, -v127
	v_fma_f32 v84, v84, v215, -v127
	v_fma_f32 v85, v85, v215, -v127
	v_fma_f32 v86, v86, v215, -v127
	v_fma_f32 v87, v87, v215, -v127
	v_fma_f32 v88, v88, v215, -v127
	v_fma_f32 v89, v89, v215, -v127
	v_fma_f32 v90, v90, v215, -v127
	v_fma_f32 v91, v91, v215, -v127
	v_fma_f32 v96, v96, v215, -v127
	v_fma_f32 v97, v97, v215, -v127
	v_fma_f32 v98, v98, v215, -v127
	v_fma_f32 v99, v99, v215, -v127
	v_exp_f32_e32 v76, v76
	v_exp_f32_e32 v77, v77
	v_exp_f32_e32 v78, v78
	v_exp_f32_e32 v79, v79
	v_exp_f32_e32 v84, v84
	v_exp_f32_e32 v85, v85
	v_exp_f32_e32 v86, v86
	v_exp_f32_e32 v87, v87
	v_exp_f32_e32 v88, v88
	v_exp_f32_e32 v89, v89
	v_exp_f32_e32 v90, v90
	v_exp_f32_e32 v91, v91
	v_exp_f32_e32 v96, v96
	v_exp_f32_e32 v97, v97
	v_exp_f32_e32 v98, v98
	v_exp_f32_e32 v99, v99
	s_nop 0
	v_mul_f32_e32 v81, v81, v124
	v_add_f32_e32 v81, v81, v76
	v_add_f32_e32 v81, v81, v77
	v_add_f32_e32 v81, v81, v78
	v_add_f32_e32 v81, v81, v79
	v_add_f32_e32 v81, v81, v84
	v_add_f32_e32 v81, v81, v85
	v_add_f32_e32 v81, v81, v86
	v_add_f32_e32 v81, v81, v87
	v_add_f32_e32 v81, v81, v88
	v_add_f32_e32 v81, v81, v89
	v_add_f32_e32 v81, v81, v90
	v_add_f32_e32 v81, v81, v91
	v_add_f32_e32 v81, v81, v96
	v_add_f32_e32 v81, v81, v97
	v_add_f32_e32 v81, v81, v98
	v_add_f32_e32 v81, v81, v99
	v_cvt_pk_bf16_f32 v164, v76, v77
	v_cvt_pk_bf16_f32 v165, v78, v79
	v_cvt_pk_bf16_f32 v166, v84, v85
	v_cvt_pk_bf16_f32 v167, v86, v87
	v_cvt_pk_bf16_f32 v168, v88, v89
	v_cvt_pk_bf16_f32 v169, v90, v91
	v_cvt_pk_bf16_f32 v170, v96, v97
	v_cvt_pk_bf16_f32 v171, v98, v99
	v_mul_f32_e32 v100, v100, v124
	v_mul_f32_e32 v101, v101, v124
	v_mul_f32_e32 v102, v102, v124
	v_mul_f32_e32 v103, v103, v124
	v_mul_f32_e32 v132, v132, v124
	v_mul_f32_e32 v133, v133, v124
	v_mul_f32_e32 v134, v134, v124
	v_mul_f32_e32 v135, v135, v124
	v_mul_f32_e32 v140, v140, v124
	v_mul_f32_e32 v141, v141, v124
	v_mul_f32_e32 v142, v142, v124
	v_mul_f32_e32 v143, v143, v124
	v_mul_f32_e32 v144, v144, v124
	v_mul_f32_e32 v145, v145, v124
	v_mul_f32_e32 v146, v146, v124
	v_mul_f32_e32 v147, v147, v124
	s_waitcnt lgkmcnt(8)
	s_nop 1
	v_mfma_f32_16x16x32_bf16 v[100:103], v[44:47], v[164:167], v[100:103]
	v_mfma_f32_16x16x32_bf16 v[132:135], v[48:51], v[164:167], v[132:135]
	v_mfma_f32_16x16x32_bf16 v[140:143], v[52:55], v[164:167], v[140:143]
	v_mfma_f32_16x16x32_bf16 v[144:147], v[56:59], v[164:167], v[144:147]
	v_mfma_f32_16x16x32_bf16 v[100:103], v[60:63], v[168:171], v[100:103]
	v_mfma_f32_16x16x32_bf16 v[132:135], v[64:67], v[168:171], v[132:135]
	v_mfma_f32_16x16x32_bf16 v[140:143], v[68:71], v[168:171], v[140:143]
	v_mfma_f32_16x16x32_bf16 v[144:147], v[72:75], v[168:171], v[144:147]
	s_nop 3
	ds_read_b128 v[44:47], v195 offset:256
	ds_read_b128 v[48:51], v195 offset:8704
	ds_read_b128 v[52:55], v195 offset:17152
	ds_read_b128 v[56:59], v195 offset:25600
	ds_read_b128 v[60:63], v195 offset:320
	ds_read_b128 v[64:67], v195 offset:8768
	ds_read_b128 v[68:71], v195 offset:17216
	ds_read_b128 v[72:75], v195 offset:25664
	s_nop 0
	s_nop 0
	s_waitcnt lgkmcnt(15)
	s_waitcnt lgkmcnt(0)
	v_mfma_f32_16x16x32_bf16 v[76:79], v[12:15], v[4:7], 0
	v_mfma_f32_16x16x32_bf16 v[76:79], v[16:19], v[8:11], v[76:79]
	v_mfma_f32_16x16x32_bf16 v[84:87], v[20:23], v[4:7], 0
	v_mfma_f32_16x16x32_bf16 v[84:87], v[24:27], v[8:11], v[84:87]
	v_mfma_f32_16x16x32_bf16 v[88:91], v[28:31], v[4:7], 0
	v_mfma_f32_16x16x32_bf16 v[88:91], v[32:35], v[8:11], v[88:91]
	v_mfma_f32_16x16x32_bf16 v[96:99], v[36:39], v[4:7], 0
	v_mfma_f32_16x16x32_bf16 v[96:99], v[40:43], v[8:11], v[96:99]
	ds_read_b128 v[12:15], v210 offset:27648
	ds_read_b128 v[16:19], v210 offset:27712
	ds_read_b128 v[20:23], v211 offset:27648
	ds_read_b128 v[24:27], v211 offset:27712
	ds_read_b128 v[28:31], v210 offset:32256
	ds_read_b128 v[32:35], v210 offset:32320
	ds_read_b128 v[36:39], v211 offset:32256
	ds_read_b128 v[40:43], v211 offset:32320
	s_nop 7
	v_mul_f32_e32 v76, 0x3e000000, v76
	v_mul_f32_e32 v77, 0x3e000000, v77
	v_mul_f32_e32 v78, 0x3e000000, v78
	v_mul_f32_e32 v79, 0x3e000000, v79
	v_mul_f32_e32 v84, 0x3e000000, v84
	v_mul_f32_e32 v85, 0x3e000000, v85
	v_mul_f32_e32 v86, 0x3e000000, v86
	v_mul_f32_e32 v87, 0x3e000000, v87
	v_mul_f32_e32 v88, 0x3e000000, v88
	v_mul_f32_e32 v89, 0x3e000000, v89
	v_mul_f32_e32 v90, 0x3e000000, v90
	v_mul_f32_e32 v91, 0x3e000000, v91
	v_mul_f32_e32 v96, 0x3e000000, v96
	v_mul_f32_e32 v97, 0x3e000000, v97
	v_mul_f32_e32 v98, 0x3e000000, v98
	v_mul_f32_e32 v99, 0x3e000000, v99
	v_max3_f32 v126, v76, v77, v78
	v_max3_f32 v128, v79, v84, v85
	v_max3_f32 v126, v126, v86, v87
	v_max3_f32 v128, v128, v88, v89
	v_max3_f32 v126, v126, v90, v91
	v_max3_f32 v128, v128, v96, v97
	v_max3_f32 v126, v126, v98, v99
	v_max_f32_e32 v126, v126, v128
	v_mov_b32_e32 v128, v126
	s_nop 1
	v_permlane32_swap_b32_e32 v128, v126
	s_nop 1
	v_max_f32_e32 v126, v126, v128
	v_mov_b32_e32 v128, v126
	s_nop 1
	v_permlane16_swap_b32_e32 v128, v126
	s_nop 1
	v_max_f32_e32 v126, v126, v128
	v_max_f32_e32 v126, v80, v126
	v_sub_f32_e32 v124, v80, v126
	v_mov_b32_e32 v80, v126
	v_mul_f32_e32 v124, 0x3fb8aa3b, v124
	v_mul_f32_e32 v127, 0x3fb8aa3b, v126
	v_exp_f32_e32 v124, v124
	v_fma_f32 v76, v76, v215, -v127
	v_fma_f32 v77, v77, v215, -v127
	v_fma_f32 v78, v78, v215, -v127
	v_fma_f32 v79, v79, v215, -v127
	v_fma_f32 v84, v84, v215, -v127
	v_fma_f32 v85, v85, v215, -v127
	v_fma_f32 v86, v86, v215, -v127
	v_fma_f32 v87, v87, v215, -v127
	v_fma_f32 v88, v88, v215, -v127
	v_fma_f32 v89, v89, v215, -v127
	v_fma_f32 v90, v90, v215, -v127
	v_fma_f32 v91, v91, v215, -v127
	v_fma_f32 v96, v96, v215, -v127
	v_fma_f32 v97, v97, v215, -v127
	v_fma_f32 v98, v98, v215, -v127
	v_fma_f32 v99, v99, v215, -v127
	v_exp_f32_e32 v76, v76
	v_exp_f32_e32 v77, v77
	v_exp_f32_e32 v78, v78
	v_exp_f32_e32 v79, v79
	v_exp_f32_e32 v84, v84
	v_exp_f32_e32 v85, v85
	v_exp_f32_e32 v86, v86
	v_exp_f32_e32 v87, v87
	v_exp_f32_e32 v88, v88
	v_exp_f32_e32 v89, v89
	v_exp_f32_e32 v90, v90
	v_exp_f32_e32 v91, v91
	v_exp_f32_e32 v96, v96
	v_exp_f32_e32 v97, v97
	v_exp_f32_e32 v98, v98
	v_exp_f32_e32 v99, v99
	s_nop 0
	v_mul_f32_e32 v81, v81, v124
	v_add_f32_e32 v81, v81, v76
	v_add_f32_e32 v81, v81, v77
	v_add_f32_e32 v81, v81, v78
	v_add_f32_e32 v81, v81, v79
	v_add_f32_e32 v81, v81, v84
	v_add_f32_e32 v81, v81, v85
	v_add_f32_e32 v81, v81, v86
	v_add_f32_e32 v81, v81, v87
	v_add_f32_e32 v81, v81, v88
	v_add_f32_e32 v81, v81, v89
	v_add_f32_e32 v81, v81, v90
	v_add_f32_e32 v81, v81, v91
	v_add_f32_e32 v81, v81, v96
	v_add_f32_e32 v81, v81, v97
	v_add_f32_e32 v81, v81, v98
	v_add_f32_e32 v81, v81, v99
	v_cvt_pk_bf16_f32 v164, v76, v77
	v_cvt_pk_bf16_f32 v165, v78, v79
	v_cvt_pk_bf16_f32 v166, v84, v85
	v_cvt_pk_bf16_f32 v167, v86, v87
	v_cvt_pk_bf16_f32 v168, v88, v89
	v_cvt_pk_bf16_f32 v169, v90, v91
	v_cvt_pk_bf16_f32 v170, v96, v97
	v_cvt_pk_bf16_f32 v171, v98, v99
	v_mul_f32_e32 v100, v100, v124
	v_mul_f32_e32 v101, v101, v124
	v_mul_f32_e32 v102, v102, v124
	v_mul_f32_e32 v103, v103, v124
	v_mul_f32_e32 v132, v132, v124
	v_mul_f32_e32 v133, v133, v124
	v_mul_f32_e32 v134, v134, v124
	v_mul_f32_e32 v135, v135, v124
	v_mul_f32_e32 v140, v140, v124
	v_mul_f32_e32 v141, v141, v124
	v_mul_f32_e32 v142, v142, v124
	v_mul_f32_e32 v143, v143, v124
	v_mul_f32_e32 v144, v144, v124
	v_mul_f32_e32 v145, v145, v124
	v_mul_f32_e32 v146, v146, v124
	v_mul_f32_e32 v147, v147, v124
	s_waitcnt lgkmcnt(8)
	s_nop 1
	v_mfma_f32_16x16x32_bf16 v[100:103], v[44:47], v[164:167], v[100:103]
	v_mfma_f32_16x16x32_bf16 v[132:135], v[48:51], v[164:167], v[132:135]
	v_mfma_f32_16x16x32_bf16 v[140:143], v[52:55], v[164:167], v[140:143]
	v_mfma_f32_16x16x32_bf16 v[144:147], v[56:59], v[164:167], v[144:147]
	v_mfma_f32_16x16x32_bf16 v[100:103], v[60:63], v[168:171], v[100:103]
	v_mfma_f32_16x16x32_bf16 v[132:135], v[64:67], v[168:171], v[132:135]
	v_mfma_f32_16x16x32_bf16 v[140:143], v[68:71], v[168:171], v[140:143]
	v_mfma_f32_16x16x32_bf16 v[144:147], v[72:75], v[168:171], v[144:147]
	s_nop 3
	ds_read_b128 v[44:47], v195 offset:384
	ds_read_b128 v[48:51], v195 offset:8832
	ds_read_b128 v[52:55], v195 offset:17280
	ds_read_b128 v[56:59], v195 offset:25728
	ds_read_b128 v[60:63], v195 offset:448
	ds_read_b128 v[64:67], v195 offset:8896
	ds_read_b128 v[68:71], v195 offset:17344
	ds_read_b128 v[72:75], v195 offset:25792
	s_nop 0
	s_nop 0
	s_waitcnt lgkmcnt(15)
	s_waitcnt lgkmcnt(0)
	v_mfma_f32_16x16x32_bf16 v[76:79], v[12:15], v[4:7], 0
	v_mfma_f32_16x16x32_bf16 v[76:79], v[16:19], v[8:11], v[76:79]
	v_mfma_f32_16x16x32_bf16 v[84:87], v[20:23], v[4:7], 0
	v_mfma_f32_16x16x32_bf16 v[84:87], v[24:27], v[8:11], v[84:87]
	v_mfma_f32_16x16x32_bf16 v[88:91], v[28:31], v[4:7], 0
	v_mfma_f32_16x16x32_bf16 v[88:91], v[32:35], v[8:11], v[88:91]
	v_mfma_f32_16x16x32_bf16 v[96:99], v[36:39], v[4:7], 0
	v_mfma_f32_16x16x32_bf16 v[96:99], v[40:43], v[8:11], v[96:99]
	s_nop 7
	v_mul_f32_e32 v76, 0x3e000000, v76
	v_mul_f32_e32 v77, 0x3e000000, v77
	v_mul_f32_e32 v78, 0x3e000000, v78
	v_mul_f32_e32 v79, 0x3e000000, v79
	v_mul_f32_e32 v84, 0x3e000000, v84
	v_mul_f32_e32 v85, 0x3e000000, v85
	v_mul_f32_e32 v86, 0x3e000000, v86
	v_mul_f32_e32 v87, 0x3e000000, v87
	v_mul_f32_e32 v88, 0x3e000000, v88
	v_mul_f32_e32 v89, 0x3e000000, v89
	v_mul_f32_e32 v90, 0x3e000000, v90
	v_mul_f32_e32 v91, 0x3e000000, v91
	v_mul_f32_e32 v96, 0x3e000000, v96
	v_mul_f32_e32 v97, 0x3e000000, v97
	v_mul_f32_e32 v98, 0x3e000000, v98
	v_mul_f32_e32 v99, 0x3e000000, v99
	v_max3_f32 v126, v76, v77, v78
	v_max3_f32 v128, v79, v84, v85
	v_max3_f32 v126, v126, v86, v87
	v_max3_f32 v128, v128, v88, v89
	v_max3_f32 v126, v126, v90, v91
	v_max3_f32 v128, v128, v96, v97
	v_max3_f32 v126, v126, v98, v99
	v_max_f32_e32 v126, v126, v128
	v_mov_b32_e32 v128, v126
	s_nop 1
	v_permlane32_swap_b32_e32 v128, v126
	s_nop 1
	v_max_f32_e32 v126, v126, v128
	v_mov_b32_e32 v128, v126
	s_nop 1
	v_permlane16_swap_b32_e32 v128, v126
	s_nop 1
	v_max_f32_e32 v126, v126, v128
	v_max_f32_e32 v126, v80, v126
	v_sub_f32_e32 v124, v80, v126
	v_mov_b32_e32 v80, v126
	v_mul_f32_e32 v124, 0x3fb8aa3b, v124
	v_mul_f32_e32 v127, 0x3fb8aa3b, v126
	v_exp_f32_e32 v124, v124
	v_fma_f32 v76, v76, v215, -v127
	v_fma_f32 v77, v77, v215, -v127
	v_fma_f32 v78, v78, v215, -v127
	v_fma_f32 v79, v79, v215, -v127
	v_fma_f32 v84, v84, v215, -v127
	v_fma_f32 v85, v85, v215, -v127
	v_fma_f32 v86, v86, v215, -v127
	v_fma_f32 v87, v87, v215, -v127
	v_fma_f32 v88, v88, v215, -v127
	v_fma_f32 v89, v89, v215, -v127
	v_fma_f32 v90, v90, v215, -v127
	v_fma_f32 v91, v91, v215, -v127
	v_fma_f32 v96, v96, v215, -v127
	v_fma_f32 v97, v97, v215, -v127
	v_fma_f32 v98, v98, v215, -v127
	v_fma_f32 v99, v99, v215, -v127
	v_exp_f32_e32 v76, v76
	v_exp_f32_e32 v77, v77
	v_exp_f32_e32 v78, v78
	v_exp_f32_e32 v79, v79
	v_exp_f32_e32 v84, v84
	v_exp_f32_e32 v85, v85
	v_exp_f32_e32 v86, v86
	v_exp_f32_e32 v87, v87
	v_exp_f32_e32 v88, v88
	v_exp_f32_e32 v89, v89
	v_exp_f32_e32 v90, v90
	v_exp_f32_e32 v91, v91
	v_exp_f32_e32 v96, v96
	v_exp_f32_e32 v97, v97
	v_exp_f32_e32 v98, v98
	v_exp_f32_e32 v99, v99
	s_nop 0
	v_mul_f32_e32 v81, v81, v124
	v_add_f32_e32 v81, v81, v76
	v_add_f32_e32 v81, v81, v77
	v_add_f32_e32 v81, v81, v78
	v_add_f32_e32 v81, v81, v79
	v_add_f32_e32 v81, v81, v84
	v_add_f32_e32 v81, v81, v85
	v_add_f32_e32 v81, v81, v86
	v_add_f32_e32 v81, v81, v87
	v_add_f32_e32 v81, v81, v88
	v_add_f32_e32 v81, v81, v89
	v_add_f32_e32 v81, v81, v90
	v_add_f32_e32 v81, v81, v91
	v_add_f32_e32 v81, v81, v96
	v_add_f32_e32 v81, v81, v97
	v_add_f32_e32 v81, v81, v98
	v_add_f32_e32 v81, v81, v99
	v_cvt_pk_bf16_f32 v164, v76, v77
	v_cvt_pk_bf16_f32 v165, v78, v79
	v_cvt_pk_bf16_f32 v166, v84, v85
	v_cvt_pk_bf16_f32 v167, v86, v87
	v_cvt_pk_bf16_f32 v168, v88, v89
	v_cvt_pk_bf16_f32 v169, v90, v91
	v_cvt_pk_bf16_f32 v170, v96, v97
	v_cvt_pk_bf16_f32 v171, v98, v99
	v_mul_f32_e32 v100, v100, v124
	v_mul_f32_e32 v101, v101, v124
	v_mul_f32_e32 v102, v102, v124
	v_mul_f32_e32 v103, v103, v124
	v_mul_f32_e32 v132, v132, v124
	v_mul_f32_e32 v133, v133, v124
	v_mul_f32_e32 v134, v134, v124
	v_mul_f32_e32 v135, v135, v124
	v_mul_f32_e32 v140, v140, v124
	v_mul_f32_e32 v141, v141, v124
	v_mul_f32_e32 v142, v142, v124
	v_mul_f32_e32 v143, v143, v124
	v_mul_f32_e32 v144, v144, v124
	v_mul_f32_e32 v145, v145, v124
	v_mul_f32_e32 v146, v146, v124
	v_mul_f32_e32 v147, v147, v124
	s_waitcnt lgkmcnt(0)
	s_nop 1
	v_mfma_f32_16x16x32_bf16 v[100:103], v[44:47], v[164:167], v[100:103]
	v_mfma_f32_16x16x32_bf16 v[132:135], v[48:51], v[164:167], v[132:135]
	v_mfma_f32_16x16x32_bf16 v[140:143], v[52:55], v[164:167], v[140:143]
	v_mfma_f32_16x16x32_bf16 v[144:147], v[56:59], v[164:167], v[144:147]
	v_mfma_f32_16x16x32_bf16 v[100:103], v[60:63], v[168:171], v[100:103]
	v_mfma_f32_16x16x32_bf16 v[132:135], v[64:67], v[168:171], v[132:135]
	v_mfma_f32_16x16x32_bf16 v[140:143], v[68:71], v[168:171], v[140:143]
	v_mfma_f32_16x16x32_bf16 v[144:147], v[72:75], v[168:171], v[144:147]
	s_nop 3
	s_nop 7
	v_mov_b32_e32 v128, v81
	s_nop 1
	v_permlane32_swap_b32_e32 v128, v81
	s_nop 1
	v_add_f32_e32 v81, v81, v128
	v_mov_b32_e32 v128, v81
	s_nop 1
	v_permlane16_swap_b32_e32 v128, v81
	s_nop 1
	v_add_f32_e32 v81, v81, v128
	v_rcp_f32_e32 v124, v81
	s_nop 0
	v_fma_f32 v126, -v81, v124, 1.0
	v_fma_f32 v124, v126, v124, v124
	v_mul_f32_e32 v100, v100, v124
	v_mul_f32_e32 v101, v101, v124
	v_mul_f32_e32 v102, v102, v124
	v_mul_f32_e32 v103, v103, v124
	v_cvt_pk_bf16_f32 v100, v100, v101
	v_cvt_pk_bf16_f32 v101, v102, v103
	global_store_dwordx2 v198, v[100:101], s[20:21] offset:0
	v_mul_f32_e32 v132, v132, v124
	v_mul_f32_e32 v133, v133, v124
	v_mul_f32_e32 v134, v134, v124
	v_mul_f32_e32 v135, v135, v124
	v_cvt_pk_bf16_f32 v132, v132, v133
	v_cvt_pk_bf16_f32 v133, v134, v135
	global_store_dwordx2 v198, v[132:133], s[20:21] offset:32
	v_mul_f32_e32 v140, v140, v124
	v_mul_f32_e32 v141, v141, v124
	v_mul_f32_e32 v142, v142, v124
	v_mul_f32_e32 v143, v143, v124
	v_cvt_pk_bf16_f32 v140, v140, v141
	v_cvt_pk_bf16_f32 v141, v142, v143
	global_store_dwordx2 v198, v[140:141], s[20:21] offset:64
	v_mul_f32_e32 v144, v144, v124
	v_mul_f32_e32 v145, v145, v124
	v_mul_f32_e32 v146, v146, v124
	v_mul_f32_e32 v147, v147, v124
	v_cvt_pk_bf16_f32 v144, v144, v145
	v_cvt_pk_bf16_f32 v145, v146, v147
	global_store_dwordx2 v198, v[144:145], s[20:21] offset:96
	s_add_i32 s89, s89, 1
	s_addk_i32 s88, 0x800
	s_cmp_eq_u32 s89, 16
	s_cbranch_scc1 .LBB0_719
	s_branch .LBB0_459
